# ret_scan rq tile: rows 0-63 by LDS-DMA and rows 64-127 through registers in one batch (single memory round trip for the whole tile)
# baseline (speedup 1.0000x reference)
.LBB0_327:
	v_mov_b32_e32 v130, s67
	v_mov_b32_e32 v131, s66
	v_cndmask_b32_e32 v130, v130, v131, vcc
	v_lshl_add_u32 v168, v130, 7, v155
	v_mov_b32_e32 v153, v161
	v_mov_b32_e32 v192, v181
	v_mov_b32_e32 v190, v183
	v_mov_b32_e32 v191, v182
	v_mov_b32_e32 v166, v157
	v_mov_b32_e32 v130, v186
	v_mov_b32_e32 v131, v187
	v_ashrrev_i32_e32 v169, 31, v168
	v_readfirstlane_b32 s64, v130
	v_readfirstlane_b32 s65, v131
	v_lshlrev_b64 v[130:131], 11, v[168:169]
	v_mov_b32_e32 v167, v189
	s_barrier
	v_lshl_add_u64 v[228:229], s[64:65], 0, v[130:131]
	v_lshl_add_u64 v[228:229], v[228:229], 0, v[0:1]
	s_mov_b32 s6, 0xc640000
	s_mov_b32 s7, 0
	v_lshl_add_u64 v[228:229], v[228:229], 0, s[6:7]
	v_and_b32_e32 v230, 0xff, v189
	v_lshrrev_b32_e32 v231, 5, v230
	v_and_b32_e32 v232, 31, v230
	v_add_u32_e32 v233, 64, v231
	v_lshlrev_b32_e32 v233, 11, v233
	v_lshl_add_u32 v226, v232, 4, v233
	v_mov_b32_e32 v227, 0
	v_lshl_add_u64 v[226:227], v[228:229], 0, v[226:227]
	v_lshrrev_b32_e32 v233, 1, v231
	v_add_u32_e32 v233, 32, v233
	v_mul_u32_u24_e32 v233, 0x410, v233
	v_and_b32_e32 v231, 1, v231
	v_lshl_add_u32 v233, v231, 9, v233
	v_lshl_add_u32 v233, v232, 4, v233
	v_add_u32_e32 v230, v149, v233
	s_mov_b32 s6, 0x4000
	global_load_dwordx4 v[130:133], v[226:227], off
	v_lshl_add_u64 v[226:227], v[226:227], 0, s[6:7]
	global_load_dwordx4 v[134:137], v[226:227], off
	v_lshl_add_u64 v[226:227], v[226:227], 0, s[6:7]
	global_load_dwordx4 v[138:141], v[226:227], off
	v_lshl_add_u64 v[226:227], v[226:227], 0, s[6:7]
	global_load_dwordx4 v[142:145], v[226:227], off
	v_lshl_add_u64 v[226:227], v[226:227], 0, s[6:7]
	global_load_dwordx4 v[170:173], v[226:227], off
	v_lshl_add_u64 v[226:227], v[226:227], 0, s[6:7]
	global_load_dwordx4 v[194:197], v[226:227], off
	v_lshl_add_u64 v[226:227], v[226:227], 0, s[6:7]
	global_load_dwordx4 v[218:221], v[226:227], off
	v_lshl_add_u64 v[226:227], v[226:227], 0, s[6:7]
	global_load_dwordx4 v[222:225], v[226:227], off
	v_bfe_u32 v231, v189, 6, 2
	v_lshlrev_b32_e32 v231, 4, v231
	v_bfe_u32 v232, v189, 5, 1
	v_add_u32_e32 v231, v231, v232
	v_lshlrev_b32_e32 v231, 11, v231
	v_and_b32_e32 v232, 31, v189
	v_lshl_add_u32 v232, v232, 4, v231
	v_mov_b32_e32 v233, 0
	v_lshl_add_u64 v[228:229], v[228:229], 0, v[232:233]
	v_readfirstlane_b32 s6, v149
	v_readfirstlane_b32 s7, v189
	s_nop 3
	s_bfe_u32 s7, s7, 0x20006
	s_mul_i32 s7, s7, 0x2080
	s_add_u32 s6, s6, s7
	s_mov_b32 m0, s6
	s_mov_b32 s6, 0x1000
	s_mov_b32 s7, 0
	global_load_lds_dwordx4 v[228:229], off
	s_add_u32 m0, m0, 0x410
	v_lshl_add_u64 v[228:229], v[228:229], 0, s[6:7]
	global_load_lds_dwordx4 v[228:229], off
	s_add_u32 m0, m0, 0x410
	v_lshl_add_u64 v[228:229], v[228:229], 0, s[6:7]
	global_load_lds_dwordx4 v[228:229], off
	s_add_u32 m0, m0, 0x410
	v_lshl_add_u64 v[228:229], v[228:229], 0, s[6:7]
	global_load_lds_dwordx4 v[228:229], off
	s_add_u32 m0, m0, 0x410
	v_lshl_add_u64 v[228:229], v[228:229], 0, s[6:7]
	global_load_lds_dwordx4 v[228:229], off
	s_add_u32 m0, m0, 0x410
	v_lshl_add_u64 v[228:229], v[228:229], 0, s[6:7]
	global_load_lds_dwordx4 v[228:229], off
	s_add_u32 m0, m0, 0x410
	v_lshl_add_u64 v[228:229], v[228:229], 0, s[6:7]
	global_load_lds_dwordx4 v[228:229], off
	s_add_u32 m0, m0, 0x410
	v_lshl_add_u64 v[228:229], v[228:229], 0, s[6:7]
	global_load_lds_dwordx4 v[228:229], off
	s_waitcnt vmcnt(15)
	ds_write2_b64 v230, v[130:131], v[132:133] offset1:1
	s_waitcnt vmcnt(14)
	v_add_u32_e32 v231, 0x1040, v230
	ds_write2_b64 v231, v[134:135], v[136:137] offset1:1
	s_waitcnt vmcnt(13)
	v_add_u32_e32 v231, 0x2080, v230
	ds_write2_b64 v231, v[138:139], v[140:141] offset1:1
	s_waitcnt vmcnt(12)
	v_add_u32_e32 v231, 0x30c0, v230
	ds_write2_b64 v231, v[142:143], v[144:145] offset1:1
	s_waitcnt vmcnt(11)
	v_add_u32_e32 v231, 0x4100, v230
	ds_write2_b64 v231, v[170:171], v[172:173] offset1:1
	s_waitcnt vmcnt(10)
	v_add_u32_e32 v231, 0x5140, v230
	ds_write2_b64 v231, v[194:195], v[196:197] offset1:1
	s_waitcnt vmcnt(9)
	v_add_u32_e32 v231, 0x6180, v230
	ds_write2_b64 v231, v[218:219], v[220:221] offset1:1
	s_waitcnt vmcnt(8)
	v_add_u32_e32 v231, 0x71c0, v230
	ds_write2_b64 v231, v[222:223], v[224:225] offset1:1
	v_lshl_add_u64 v[210:211], s[64:65], 0, v[162:163]
	s_waitcnt vmcnt(0)
	s_waitcnt lgkmcnt(0)
	s_barrier
	v_ashrrev_i32_e32 v167, 31, v166
	v_lshl_add_u64 v[130:131], v[166:167], 1, v[210:211]
	s_mov_b64 s[6:7], 0x8640000
	v_lshl_add_u64 v[170:171], v[130:131], 0, s[6:7]
	v_add_u32_e32 v250, 0x4000, v178
	ds_read2_b64 v[194:197], v178 offset0:0 offset1:2
	ds_read2_b64 v[218:221], v250 offset0:32 offset1:34
	ds_read2_b64 v[222:225], v178 offset0:4 offset1:6
	ds_read2_b64 v[226:229], v250 offset0:36 offset1:38
	s_nop 0
	v_cvt_pk_bf16_f32 v230, v2, v3
	v_cvt_pk_bf16_f32 v231, v4, v5
	v_cvt_pk_bf16_f32 v232, v6, v7
	v_cvt_pk_bf16_f32 v233, v8, v9
	s_waitcnt lgkmcnt(2)
	s_nop 1
	v_mfma_f32_32x32x16_bf16 v[130:145], v[194:197], v[230:233], 0
	v_mfma_f32_32x32x16_bf16 v[234:249], v[218:221], v[230:233], 0
	ds_read2_b64 v[194:197], v178 offset0:8 offset1:10
	ds_read2_b64 v[218:221], v250 offset0:40 offset1:42
	s_nop 0
	v_cvt_pk_bf16_f32 v230, v10, v11
	v_cvt_pk_bf16_f32 v231, v12, v13
	v_cvt_pk_bf16_f32 v232, v14, v15
	v_cvt_pk_bf16_f32 v233, v16, v17
	s_waitcnt lgkmcnt(2)
	s_nop 1
	v_mfma_f32_32x32x16_bf16 v[130:145], v[222:225], v[230:233], v[130:145]
	v_mfma_f32_32x32x16_bf16 v[234:249], v[226:229], v[230:233], v[234:249]
	ds_read2_b64 v[222:225], v178 offset0:12 offset1:14
	ds_read2_b64 v[226:229], v250 offset0:44 offset1:46
	s_nop 0
	v_cvt_pk_bf16_f32 v230, v18, v19
	v_cvt_pk_bf16_f32 v231, v20, v21
	v_cvt_pk_bf16_f32 v232, v22, v23
	v_cvt_pk_bf16_f32 v233, v24, v25
	s_waitcnt lgkmcnt(2)
	s_nop 1
	v_mfma_f32_32x32x16_bf16 v[130:145], v[194:197], v[230:233], v[130:145]
	v_mfma_f32_32x32x16_bf16 v[234:249], v[218:221], v[230:233], v[234:249]
	ds_read2_b64 v[194:197], v178 offset0:16 offset1:18
	ds_read2_b64 v[218:221], v250 offset0:48 offset1:50
	s_nop 0
	v_cvt_pk_bf16_f32 v230, v26, v27
	v_cvt_pk_bf16_f32 v231, v28, v29
	v_cvt_pk_bf16_f32 v232, v30, v31
	v_cvt_pk_bf16_f32 v233, v32, v33
	s_waitcnt lgkmcnt(2)
	s_nop 1
	v_mfma_f32_32x32x16_bf16 v[130:145], v[222:225], v[230:233], v[130:145]
	v_mfma_f32_32x32x16_bf16 v[234:249], v[226:229], v[230:233], v[234:249]
	ds_read2_b64 v[222:225], v178 offset0:20 offset1:22
	ds_read2_b64 v[226:229], v250 offset0:52 offset1:54
	s_nop 0
	v_cvt_pk_bf16_f32 v230, v34, v35
	v_cvt_pk_bf16_f32 v231, v36, v37
	v_cvt_pk_bf16_f32 v232, v38, v39
	v_cvt_pk_bf16_f32 v233, v40, v41
	s_waitcnt lgkmcnt(2)
	s_nop 1
	v_mfma_f32_32x32x16_bf16 v[130:145], v[194:197], v[230:233], v[130:145]
	v_mfma_f32_32x32x16_bf16 v[234:249], v[218:221], v[230:233], v[234:249]
	ds_read2_b64 v[194:197], v178 offset0:24 offset1:26
	ds_read2_b64 v[218:221], v250 offset0:56 offset1:58
	s_nop 0
	v_cvt_pk_bf16_f32 v230, v42, v43
	v_cvt_pk_bf16_f32 v231, v44, v45
	v_cvt_pk_bf16_f32 v232, v46, v47
	v_cvt_pk_bf16_f32 v233, v48, v49
	s_waitcnt lgkmcnt(2)
	s_nop 1
	v_mfma_f32_32x32x16_bf16 v[130:145], v[222:225], v[230:233], v[130:145]
	v_mfma_f32_32x32x16_bf16 v[234:249], v[226:229], v[230:233], v[234:249]
	ds_read2_b64 v[222:225], v178 offset0:28 offset1:30
	ds_read2_b64 v[226:229], v250 offset0:60 offset1:62
	s_nop 0
	v_cvt_pk_bf16_f32 v230, v50, v51
	v_cvt_pk_bf16_f32 v231, v52, v53
	v_cvt_pk_bf16_f32 v232, v54, v55
	v_cvt_pk_bf16_f32 v233, v56, v57
	s_waitcnt lgkmcnt(2)
	s_nop 1
	v_mfma_f32_32x32x16_bf16 v[130:145], v[194:197], v[230:233], v[130:145]
	v_mfma_f32_32x32x16_bf16 v[234:249], v[218:221], v[230:233], v[234:249]
	ds_read2_b64 v[194:197], v178 offset0:32 offset1:34
	ds_read2_b64 v[218:221], v250 offset0:64 offset1:66
	s_nop 0
	v_cvt_pk_bf16_f32 v230, v58, v59
	v_cvt_pk_bf16_f32 v231, v60, v61
	v_cvt_pk_bf16_f32 v232, v62, v63
	v_cvt_pk_bf16_f32 v233, v64, v65
	s_waitcnt lgkmcnt(2)
	s_nop 1
	v_mfma_f32_32x32x16_bf16 v[130:145], v[222:225], v[230:233], v[130:145]
	v_mfma_f32_32x32x16_bf16 v[234:249], v[226:229], v[230:233], v[234:249]
	ds_read2_b64 v[222:225], v178 offset0:36 offset1:38
	ds_read2_b64 v[226:229], v250 offset0:68 offset1:70
	s_nop 0
	v_cvt_pk_bf16_f32 v230, v66, v67
	v_cvt_pk_bf16_f32 v231, v68, v69
	v_cvt_pk_bf16_f32 v232, v70, v71
	v_cvt_pk_bf16_f32 v233, v72, v73
	s_waitcnt lgkmcnt(2)
	s_nop 1
	v_mfma_f32_32x32x16_bf16 v[130:145], v[194:197], v[230:233], v[130:145]
	v_mfma_f32_32x32x16_bf16 v[234:249], v[218:221], v[230:233], v[234:249]
	ds_read2_b64 v[194:197], v178 offset0:40 offset1:42
	ds_read2_b64 v[218:221], v250 offset0:72 offset1:74
	s_nop 0
	v_cvt_pk_bf16_f32 v230, v74, v75
	v_cvt_pk_bf16_f32 v231, v76, v77
	v_cvt_pk_bf16_f32 v232, v78, v79
	v_cvt_pk_bf16_f32 v233, v80, v81
	s_waitcnt lgkmcnt(2)
	s_nop 1
	v_mfma_f32_32x32x16_bf16 v[130:145], v[222:225], v[230:233], v[130:145]
	v_mfma_f32_32x32x16_bf16 v[234:249], v[226:229], v[230:233], v[234:249]
	ds_read2_b64 v[222:225], v178 offset0:44 offset1:46
	ds_read2_b64 v[226:229], v250 offset0:76 offset1:78
	s_nop 0
	v_cvt_pk_bf16_f32 v230, v82, v83
	v_cvt_pk_bf16_f32 v231, v84, v85
	v_cvt_pk_bf16_f32 v232, v86, v87
	v_cvt_pk_bf16_f32 v233, v88, v89
	s_waitcnt lgkmcnt(2)
	s_nop 1
	v_mfma_f32_32x32x16_bf16 v[130:145], v[194:197], v[230:233], v[130:145]
	v_mfma_f32_32x32x16_bf16 v[234:249], v[218:221], v[230:233], v[234:249]
	ds_read2_b64 v[194:197], v178 offset0:48 offset1:50
	ds_read2_b64 v[218:221], v250 offset0:80 offset1:82
	s_nop 0
	v_cvt_pk_bf16_f32 v230, v90, v91
	v_cvt_pk_bf16_f32 v231, v92, v93
	v_cvt_pk_bf16_f32 v232, v94, v95
	v_cvt_pk_bf16_f32 v233, v96, v97
	s_waitcnt lgkmcnt(2)
	s_nop 1
	v_mfma_f32_32x32x16_bf16 v[130:145], v[222:225], v[230:233], v[130:145]
	v_mfma_f32_32x32x16_bf16 v[234:249], v[226:229], v[230:233], v[234:249]
	ds_read2_b64 v[222:225], v178 offset0:52 offset1:54
	ds_read2_b64 v[226:229], v250 offset0:84 offset1:86
	s_nop 0
	v_cvt_pk_bf16_f32 v230, v98, v99
	v_cvt_pk_bf16_f32 v231, v100, v101
	v_cvt_pk_bf16_f32 v232, v102, v103
	v_cvt_pk_bf16_f32 v233, v104, v105
	s_waitcnt lgkmcnt(2)
	s_nop 1
	v_mfma_f32_32x32x16_bf16 v[130:145], v[194:197], v[230:233], v[130:145]
	v_mfma_f32_32x32x16_bf16 v[234:249], v[218:221], v[230:233], v[234:249]
	ds_read2_b64 v[194:197], v178 offset0:56 offset1:58
	ds_read2_b64 v[218:221], v250 offset0:88 offset1:90
	s_nop 0
	v_cvt_pk_bf16_f32 v230, v106, v107
	v_cvt_pk_bf16_f32 v231, v108, v109
	v_cvt_pk_bf16_f32 v232, v110, v111
	v_cvt_pk_bf16_f32 v233, v112, v113
	s_waitcnt lgkmcnt(2)
	s_nop 1
	v_mfma_f32_32x32x16_bf16 v[130:145], v[222:225], v[230:233], v[130:145]
	v_mfma_f32_32x32x16_bf16 v[234:249], v[226:229], v[230:233], v[234:249]
	ds_read2_b64 v[222:225], v178 offset0:60 offset1:62
	ds_read2_b64 v[226:229], v250 offset0:92 offset1:94
	s_nop 0
	v_cvt_pk_bf16_f32 v230, v114, v115
	v_cvt_pk_bf16_f32 v231, v116, v117
	v_cvt_pk_bf16_f32 v232, v118, v119
	v_cvt_pk_bf16_f32 v233, v120, v121
	s_waitcnt lgkmcnt(2)
	s_nop 1
	v_mfma_f32_32x32x16_bf16 v[130:145], v[194:197], v[230:233], v[130:145]
	v_mfma_f32_32x32x16_bf16 v[234:249], v[218:221], v[230:233], v[234:249]
	s_nop 0
	v_cvt_pk_bf16_f32 v230, v122, v123
	v_cvt_pk_bf16_f32 v231, v124, v125
	v_cvt_pk_bf16_f32 v232, v126, v127
	v_cvt_pk_bf16_f32 v233, v128, v129
	s_waitcnt lgkmcnt(0)
	s_nop 1
	v_mfma_f32_32x32x16_bf16 v[130:145], v[222:225], v[230:233], v[130:145]
	v_mfma_f32_32x32x16_bf16 v[234:249], v[226:229], v[230:233], v[234:249]
	v_or_b32_e32 v172, v168, v174
	v_ashrrev_i32_e32 v173, 31, v172
	v_fma_f32 v193, 0, v192, v153
	v_exp_f32_e32 v193, v193
	v_lshlrev_b64 v[172:173], 12, v[172:173]
	v_lshl_add_u64 v[194:195], v[170:171], 0, v[172:173]
	s_nop 7
	v_mul_f32_e32 v130, v193, v130
	v_mov_b32_e32 v251, 0x7fff
	v_bfe_u32 v250, v130, 16, 1
	v_add3_u32 v130, v130, v250, v251
	global_store_short_d16_hi v[194:195], v130, off
	v_add_f32_e32 v130, v153, v192
	v_exp_f32_e32 v130, v130
	s_nop 0
	v_mul_f32_e32 v130, v130, v131
	v_bfe_u32 v250, v130, 16, 1
	v_add3_u32 v193, v130, v250, v251
	v_or_b32_e32 v130, 0x1000, v172
	v_mov_b32_e32 v131, v173
	v_lshl_add_u64 v[130:131], v[170:171], 0, v[130:131]
	global_store_short_d16_hi v[130:131], v193, off
	v_fma_f32 v130, 2.0, v192, v153
	v_exp_f32_e32 v130, v130
	v_mov_b32_e32 v131, v173
	v_mul_f32_e32 v130, v130, v132
	v_bfe_u32 v250, v130, 16, 1
	v_add3_u32 v132, v130, v250, v251
	v_or_b32_e32 v130, 0x2000, v172
	v_lshl_add_u64 v[130:131], v[170:171], 0, v[130:131]
	global_store_short_d16_hi v[130:131], v132, off
	v_fmamk_f32 v130, v192, 0x40400000, v153
	v_exp_f32_e32 v130, v130
	v_mov_b32_e32 v131, v173
	v_mul_f32_e32 v130, v130, v133
	v_bfe_u32 v250, v130, 16, 1
	v_add3_u32 v132, v130, v250, v251
	v_or_b32_e32 v130, 0x3000, v172
	v_lshl_add_u64 v[130:131], v[170:171], 0, v[130:131]
	global_store_short_d16_hi v[130:131], v132, off
	v_fmamk_f32 v130, v192, 0x41000000, v153
	v_exp_f32_e32 v130, v130
	v_mov_b32_e32 v131, v173
	v_mul_f32_e32 v130, v130, v134
	v_bfe_u32 v250, v130, 16, 1
	v_add3_u32 v132, v130, v250, v251
	v_or_b32_e32 v130, 0x8000, v172
	v_lshl_add_u64 v[130:131], v[170:171], 0, v[130:131]
	global_store_short_d16_hi v[130:131], v132, off
	v_fmamk_f32 v130, v192, 0x41100000, v153
	v_exp_f32_e32 v130, v130
	v_mov_b32_e32 v131, v173
	v_mul_f32_e32 v130, v130, v135
	v_bfe_u32 v250, v130, 16, 1
	v_add3_u32 v132, v130, v250, v251
	v_or_b32_e32 v130, 0x9000, v172
	v_lshl_add_u64 v[130:131], v[170:171], 0, v[130:131]
	global_store_short_d16_hi v[130:131], v132, off
	v_fmamk_f32 v130, v192, 0x41200000, v153
	v_exp_f32_e32 v130, v130
	v_mov_b32_e32 v131, v173
	v_mul_f32_e32 v130, v130, v136
	v_bfe_u32 v250, v130, 16, 1
	v_add3_u32 v132, v130, v250, v251
	v_or_b32_e32 v130, 0xa000, v172
	v_lshl_add_u64 v[130:131], v[170:171], 0, v[130:131]
	global_store_short_d16_hi v[130:131], v132, off
	v_fmamk_f32 v130, v192, 0x41300000, v153
	v_exp_f32_e32 v130, v130
	v_mov_b32_e32 v131, v173
	v_mul_f32_e32 v130, v130, v137
	v_bfe_u32 v250, v130, 16, 1
	v_add3_u32 v132, v130, v250, v251
	v_or_b32_e32 v130, 0xb000, v172
	v_lshl_add_u64 v[130:131], v[170:171], 0, v[130:131]
	global_store_short_d16_hi v[130:131], v132, off
	v_fmamk_f32 v130, v192, 0x41800000, v153
	v_exp_f32_e32 v130, v130
	v_mov_b32_e32 v131, v173
	v_mul_f32_e32 v130, v130, v138
	v_bfe_u32 v250, v130, 16, 1
	v_add3_u32 v132, v130, v250, v251
	v_or_b32_e32 v130, 0x10000, v172
	v_lshl_add_u64 v[130:131], v[170:171], 0, v[130:131]
	global_store_short_d16_hi v[130:131], v132, off
	v_fmamk_f32 v130, v192, 0x41880000, v153
	v_exp_f32_e32 v130, v130
	v_mov_b32_e32 v131, v173
	v_mul_f32_e32 v130, v130, v139
	v_bfe_u32 v250, v130, 16, 1
	v_add3_u32 v132, v130, v250, v251
	v_or_b32_e32 v130, 0x11000, v172
	v_lshl_add_u64 v[130:131], v[170:171], 0, v[130:131]
	global_store_short_d16_hi v[130:131], v132, off
	v_fmamk_f32 v130, v192, 0x41900000, v153
	v_exp_f32_e32 v130, v130
	v_mov_b32_e32 v131, v173
	v_mul_f32_e32 v130, v130, v140
	v_bfe_u32 v250, v130, 16, 1
	v_add3_u32 v132, v130, v250, v251
	v_or_b32_e32 v130, 0x12000, v172
	v_lshl_add_u64 v[130:131], v[170:171], 0, v[130:131]
	global_store_short_d16_hi v[130:131], v132, off
	v_fmamk_f32 v130, v192, 0x41980000, v153
	v_exp_f32_e32 v130, v130
	v_mov_b32_e32 v131, v173
	v_mul_f32_e32 v130, v130, v141
	v_bfe_u32 v250, v130, 16, 1
	v_add3_u32 v132, v130, v250, v251
	v_or_b32_e32 v130, 0x13000, v172
	v_lshl_add_u64 v[130:131], v[170:171], 0, v[130:131]
	global_store_short_d16_hi v[130:131], v132, off
	v_fmamk_f32 v130, v192, 0x41c00000, v153
	v_exp_f32_e32 v130, v130
	v_mov_b32_e32 v131, v173
	v_mul_f32_e32 v130, v130, v142
	v_bfe_u32 v250, v130, 16, 1
	v_add3_u32 v132, v130, v250, v251
	v_or_b32_e32 v130, 0x18000, v172
	v_lshl_add_u64 v[130:131], v[170:171], 0, v[130:131]
	global_store_short_d16_hi v[130:131], v132, off
	v_fmamk_f32 v130, v192, 0x41c80000, v153
	v_exp_f32_e32 v130, v130
	v_mov_b32_e32 v131, v173
	v_mul_f32_e32 v130, v130, v143
	v_bfe_u32 v250, v130, 16, 1
	v_add3_u32 v132, v130, v250, v251
	v_or_b32_e32 v130, 0x19000, v172
	v_lshl_add_u64 v[130:131], v[170:171], 0, v[130:131]
	global_store_short_d16_hi v[130:131], v132, off
	v_fmamk_f32 v130, v192, 0x41d00000, v153
	v_exp_f32_e32 v130, v130
	v_mov_b32_e32 v131, v173
	v_mul_f32_e32 v130, v130, v144
	v_bfe_u32 v250, v130, 16, 1
	v_add3_u32 v132, v130, v250, v251
	v_or_b32_e32 v130, 0x1a000, v172
	v_lshl_add_u64 v[130:131], v[170:171], 0, v[130:131]
	global_store_short_d16_hi v[130:131], v132, off
	v_fmamk_f32 v130, v192, 0x41d80000, v153
	v_exp_f32_e32 v130, v130
	v_mov_b32_e32 v131, v173
	v_mul_f32_e32 v130, v130, v145
	v_bfe_u32 v250, v130, 16, 1
	v_add3_u32 v132, v130, v250, v251
	v_or_b32_e32 v130, 0x1b000, v172
	v_lshl_add_u64 v[130:131], v[170:171], 0, v[130:131]
	global_store_short_d16_hi v[130:131], v132, off
	v_mov_b32_e32 v130, v234
	v_mov_b32_e32 v131, v235
	v_mov_b32_e32 v132, v236
	v_mov_b32_e32 v133, v237
	v_mov_b32_e32 v134, v238
	v_mov_b32_e32 v135, v239
	v_mov_b32_e32 v136, v240
	v_mov_b32_e32 v137, v241
	v_mov_b32_e32 v138, v242
	v_mov_b32_e32 v139, v243
	v_mov_b32_e32 v140, v244
	v_mov_b32_e32 v141, v245
	v_mov_b32_e32 v142, v246
	v_mov_b32_e32 v143, v247
	v_mov_b32_e32 v144, v248
	v_mov_b32_e32 v145, v249
	v_fmamk_f32 v193, v192, 0x42000000, v153
	v_exp_f32_e32 v193, v193
	v_or_b32_e32 v194, 0x20000, v172
	v_mov_b32_e32 v195, v173
	v_lshl_add_u64 v[194:195], v[170:171], 0, v[194:195]
	s_nop 6
	v_mul_f32_e32 v130, v193, v130
	v_mov_b32_e32 v251, 0x7fff
	v_bfe_u32 v250, v130, 16, 1
	v_add3_u32 v130, v130, v250, v251
	global_store_short_d16_hi v[194:195], v130, off
	v_fmamk_f32 v130, v192, 0x42040000, v153
	v_exp_f32_e32 v130, v130
	s_nop 0
	v_mul_f32_e32 v130, v130, v131
	v_bfe_u32 v250, v130, 16, 1
	v_add3_u32 v193, v130, v250, v251
	v_or_b32_e32 v130, 0x21000, v172
	v_mov_b32_e32 v131, v173
	v_lshl_add_u64 v[130:131], v[170:171], 0, v[130:131]
	global_store_short_d16_hi v[130:131], v193, off
	v_fmamk_f32 v130, v192, 0x42080000, v153
	v_exp_f32_e32 v130, v130
	v_mov_b32_e32 v131, v173
	v_mul_f32_e32 v130, v130, v132
	v_bfe_u32 v250, v130, 16, 1
	v_add3_u32 v132, v130, v250, v251
	v_or_b32_e32 v130, 0x22000, v172
	v_lshl_add_u64 v[130:131], v[170:171], 0, v[130:131]
	global_store_short_d16_hi v[130:131], v132, off
	v_fmamk_f32 v130, v192, 0x420c0000, v153
	v_exp_f32_e32 v130, v130
	v_mov_b32_e32 v131, v173
	v_mul_f32_e32 v130, v130, v133
	v_bfe_u32 v250, v130, 16, 1
	v_add3_u32 v132, v130, v250, v251
	v_or_b32_e32 v130, 0x23000, v172
	v_lshl_add_u64 v[130:131], v[170:171], 0, v[130:131]
	global_store_short_d16_hi v[130:131], v132, off
	v_fmamk_f32 v130, v192, 0x42200000, v153
	v_exp_f32_e32 v130, v130
	v_mov_b32_e32 v131, v173
	v_mul_f32_e32 v130, v130, v134
	v_bfe_u32 v250, v130, 16, 1
	v_add3_u32 v132, v130, v250, v251
	v_or_b32_e32 v130, 0x28000, v172
	v_lshl_add_u64 v[130:131], v[170:171], 0, v[130:131]
	global_store_short_d16_hi v[130:131], v132, off
	v_fmamk_f32 v130, v192, 0x42240000, v153
	v_exp_f32_e32 v130, v130
	v_mov_b32_e32 v131, v173
	v_mul_f32_e32 v130, v130, v135
	v_bfe_u32 v250, v130, 16, 1
	v_add3_u32 v132, v130, v250, v251
	v_or_b32_e32 v130, 0x29000, v172
	v_lshl_add_u64 v[130:131], v[170:171], 0, v[130:131]
	global_store_short_d16_hi v[130:131], v132, off
	v_fmamk_f32 v130, v192, 0x42280000, v153
	v_exp_f32_e32 v130, v130
	v_mov_b32_e32 v131, v173
	v_mul_f32_e32 v130, v130, v136
	v_bfe_u32 v250, v130, 16, 1
	v_add3_u32 v132, v130, v250, v251
	v_or_b32_e32 v130, 0x2a000, v172
	v_lshl_add_u64 v[130:131], v[170:171], 0, v[130:131]
	global_store_short_d16_hi v[130:131], v132, off
	v_fmamk_f32 v130, v192, 0x422c0000, v153
	v_exp_f32_e32 v130, v130
	v_mov_b32_e32 v131, v173
	v_mul_f32_e32 v130, v130, v137
	v_bfe_u32 v250, v130, 16, 1
	v_add3_u32 v132, v130, v250, v251
	v_or_b32_e32 v130, 0x2b000, v172
	v_lshl_add_u64 v[130:131], v[170:171], 0, v[130:131]
	global_store_short_d16_hi v[130:131], v132, off
	v_fmamk_f32 v130, v192, 0x42400000, v153
	v_exp_f32_e32 v130, v130
	v_mov_b32_e32 v131, v173
	v_mul_f32_e32 v130, v130, v138
	v_bfe_u32 v250, v130, 16, 1
	v_add3_u32 v132, v130, v250, v251
	v_or_b32_e32 v130, 0x30000, v172
	v_lshl_add_u64 v[130:131], v[170:171], 0, v[130:131]
	global_store_short_d16_hi v[130:131], v132, off
	v_fmamk_f32 v130, v192, 0x42440000, v153
	v_exp_f32_e32 v130, v130
	v_mov_b32_e32 v131, v173
	v_mul_f32_e32 v130, v130, v139
	v_bfe_u32 v250, v130, 16, 1
	v_add3_u32 v132, v130, v250, v251
	v_or_b32_e32 v130, 0x31000, v172
	v_lshl_add_u64 v[130:131], v[170:171], 0, v[130:131]
	global_store_short_d16_hi v[130:131], v132, off
	v_fmamk_f32 v130, v192, 0x42480000, v153
	v_exp_f32_e32 v130, v130
	v_mov_b32_e32 v131, v173
	v_mul_f32_e32 v130, v130, v140
	v_bfe_u32 v250, v130, 16, 1
	v_add3_u32 v132, v130, v250, v251
	v_or_b32_e32 v130, 0x32000, v172
	v_lshl_add_u64 v[130:131], v[170:171], 0, v[130:131]
	global_store_short_d16_hi v[130:131], v132, off
	v_fmamk_f32 v130, v192, 0x424c0000, v153
	v_exp_f32_e32 v130, v130
	v_mov_b32_e32 v131, v173
	v_mul_f32_e32 v130, v130, v141
	v_bfe_u32 v250, v130, 16, 1
	v_add3_u32 v132, v130, v250, v251
	v_or_b32_e32 v130, 0x33000, v172
	v_lshl_add_u64 v[130:131], v[170:171], 0, v[130:131]
	global_store_short_d16_hi v[130:131], v132, off
	v_fmamk_f32 v130, v192, 0x42600000, v153
	v_exp_f32_e32 v130, v130
	v_mov_b32_e32 v131, v173
	v_mul_f32_e32 v130, v130, v142
	v_bfe_u32 v250, v130, 16, 1
	v_add3_u32 v132, v130, v250, v251
	v_or_b32_e32 v130, 0x38000, v172
	v_lshl_add_u64 v[130:131], v[170:171], 0, v[130:131]
	global_store_short_d16_hi v[130:131], v132, off
	v_fmamk_f32 v130, v192, 0x42640000, v153
	v_exp_f32_e32 v130, v130
	v_mov_b32_e32 v131, v173
	v_mul_f32_e32 v130, v130, v143
	v_bfe_u32 v250, v130, 16, 1
	v_add3_u32 v132, v130, v250, v251
	v_or_b32_e32 v130, 0x39000, v172
	v_lshl_add_u64 v[130:131], v[170:171], 0, v[130:131]
	global_store_short_d16_hi v[130:131], v132, off
	v_fmamk_f32 v130, v192, 0x42680000, v153
	v_exp_f32_e32 v130, v130
	v_mov_b32_e32 v131, v173
	v_mul_f32_e32 v130, v130, v144
	v_bfe_u32 v250, v130, 16, 1
	v_add3_u32 v132, v130, v250, v251
	v_or_b32_e32 v130, 0x3a000, v172
	v_lshl_add_u64 v[130:131], v[170:171], 0, v[130:131]
	global_store_short_d16_hi v[130:131], v132, off
	v_fmamk_f32 v130, v192, 0x426c0000, v153
	v_exp_f32_e32 v130, v130
	v_mov_b32_e32 v131, v173
	v_mul_f32_e32 v130, v130, v145
	v_bfe_u32 v250, v130, 16, 1
	v_add3_u32 v132, v130, v250, v251
	v_or_b32_e32 v130, 0x3b000, v172
	v_lshl_add_u64 v[130:131], v[170:171], 0, v[130:131]
	global_store_short_d16_hi v[130:131], v132, off
	v_add_u32_e32 v250, 0xc000, v178
	v_add_u32_e32 v251, 0x8000, v178
	ds_read2_b64 v[194:197], v251 offset0:64 offset1:66
	ds_read2_b64 v[218:221], v250 offset0:96 offset1:98
	ds_read2_b64 v[222:225], v251 offset0:68 offset1:70
	ds_read2_b64 v[226:229], v250 offset0:100 offset1:102
	s_nop 0
	v_cvt_pk_bf16_f32 v230, v2, v3
	v_cvt_pk_bf16_f32 v231, v4, v5
	v_cvt_pk_bf16_f32 v232, v6, v7
	v_cvt_pk_bf16_f32 v233, v8, v9
	s_waitcnt lgkmcnt(2)
	s_nop 1
	v_mfma_f32_32x32x16_bf16 v[130:145], v[194:197], v[230:233], 0
	v_mfma_f32_32x32x16_bf16 v[234:249], v[218:221], v[230:233], 0
	ds_read2_b64 v[194:197], v251 offset0:72 offset1:74
	ds_read2_b64 v[218:221], v250 offset0:104 offset1:106
	s_nop 0
	v_cvt_pk_bf16_f32 v230, v10, v11
	v_cvt_pk_bf16_f32 v231, v12, v13
	v_cvt_pk_bf16_f32 v232, v14, v15
	v_cvt_pk_bf16_f32 v233, v16, v17
	s_waitcnt lgkmcnt(2)
	s_nop 1
	v_mfma_f32_32x32x16_bf16 v[130:145], v[222:225], v[230:233], v[130:145]
	v_mfma_f32_32x32x16_bf16 v[234:249], v[226:229], v[230:233], v[234:249]
	ds_read2_b64 v[222:225], v251 offset0:76 offset1:78
	ds_read2_b64 v[226:229], v250 offset0:108 offset1:110
	s_nop 0
	v_cvt_pk_bf16_f32 v230, v18, v19
	v_cvt_pk_bf16_f32 v231, v20, v21
	v_cvt_pk_bf16_f32 v232, v22, v23
	v_cvt_pk_bf16_f32 v233, v24, v25
	s_waitcnt lgkmcnt(2)
	s_nop 1
	v_mfma_f32_32x32x16_bf16 v[130:145], v[194:197], v[230:233], v[130:145]
	v_mfma_f32_32x32x16_bf16 v[234:249], v[218:221], v[230:233], v[234:249]
	ds_read2_b64 v[194:197], v251 offset0:80 offset1:82
	ds_read2_b64 v[218:221], v250 offset0:112 offset1:114
	s_nop 0
	v_cvt_pk_bf16_f32 v230, v26, v27
	v_cvt_pk_bf16_f32 v231, v28, v29
	v_cvt_pk_bf16_f32 v232, v30, v31
	v_cvt_pk_bf16_f32 v233, v32, v33
	s_waitcnt lgkmcnt(2)
	s_nop 1
	v_mfma_f32_32x32x16_bf16 v[130:145], v[222:225], v[230:233], v[130:145]
	v_mfma_f32_32x32x16_bf16 v[234:249], v[226:229], v[230:233], v[234:249]
	ds_read2_b64 v[222:225], v251 offset0:84 offset1:86
	ds_read2_b64 v[226:229], v250 offset0:116 offset1:118
	s_nop 0
	v_cvt_pk_bf16_f32 v230, v34, v35
	v_cvt_pk_bf16_f32 v231, v36, v37
	v_cvt_pk_bf16_f32 v232, v38, v39
	v_cvt_pk_bf16_f32 v233, v40, v41
	s_waitcnt lgkmcnt(2)
	s_nop 1
	v_mfma_f32_32x32x16_bf16 v[130:145], v[194:197], v[230:233], v[130:145]
	v_mfma_f32_32x32x16_bf16 v[234:249], v[218:221], v[230:233], v[234:249]
	ds_read2_b64 v[194:197], v251 offset0:88 offset1:90
	ds_read2_b64 v[218:221], v250 offset0:120 offset1:122
	s_nop 0
	v_cvt_pk_bf16_f32 v230, v42, v43
	v_cvt_pk_bf16_f32 v231, v44, v45
	v_cvt_pk_bf16_f32 v232, v46, v47
	v_cvt_pk_bf16_f32 v233, v48, v49
	s_waitcnt lgkmcnt(2)
	s_nop 1
	v_mfma_f32_32x32x16_bf16 v[130:145], v[222:225], v[230:233], v[130:145]
	v_mfma_f32_32x32x16_bf16 v[234:249], v[226:229], v[230:233], v[234:249]
	ds_read2_b64 v[222:225], v251 offset0:92 offset1:94
	ds_read2_b64 v[226:229], v250 offset0:124 offset1:126
	s_nop 0
	v_cvt_pk_bf16_f32 v230, v50, v51
	v_cvt_pk_bf16_f32 v231, v52, v53
	v_cvt_pk_bf16_f32 v232, v54, v55
	v_cvt_pk_bf16_f32 v233, v56, v57
	s_waitcnt lgkmcnt(2)
	s_nop 1
	v_mfma_f32_32x32x16_bf16 v[130:145], v[194:197], v[230:233], v[130:145]
	v_mfma_f32_32x32x16_bf16 v[234:249], v[218:221], v[230:233], v[234:249]
	ds_read2_b64 v[194:197], v251 offset0:96 offset1:98
	ds_read2_b64 v[218:221], v250 offset0:128 offset1:130
	s_nop 0
	v_cvt_pk_bf16_f32 v230, v58, v59
	v_cvt_pk_bf16_f32 v231, v60, v61
	v_cvt_pk_bf16_f32 v232, v62, v63
	v_cvt_pk_bf16_f32 v233, v64, v65
	s_waitcnt lgkmcnt(2)
	s_nop 1
	v_mfma_f32_32x32x16_bf16 v[130:145], v[222:225], v[230:233], v[130:145]
	v_mfma_f32_32x32x16_bf16 v[234:249], v[226:229], v[230:233], v[234:249]
	ds_read2_b64 v[222:225], v251 offset0:100 offset1:102
	ds_read2_b64 v[226:229], v250 offset0:132 offset1:134
	s_nop 0
	v_cvt_pk_bf16_f32 v230, v66, v67
	v_cvt_pk_bf16_f32 v231, v68, v69
	v_cvt_pk_bf16_f32 v232, v70, v71
	v_cvt_pk_bf16_f32 v233, v72, v73
	s_waitcnt lgkmcnt(2)
	s_nop 1
	v_mfma_f32_32x32x16_bf16 v[130:145], v[194:197], v[230:233], v[130:145]
	v_mfma_f32_32x32x16_bf16 v[234:249], v[218:221], v[230:233], v[234:249]
	ds_read2_b64 v[194:197], v251 offset0:104 offset1:106
	ds_read2_b64 v[218:221], v250 offset0:136 offset1:138
	s_nop 0
	v_cvt_pk_bf16_f32 v230, v74, v75
	v_cvt_pk_bf16_f32 v231, v76, v77
	v_cvt_pk_bf16_f32 v232, v78, v79
	v_cvt_pk_bf16_f32 v233, v80, v81
	s_waitcnt lgkmcnt(2)
	s_nop 1
	v_mfma_f32_32x32x16_bf16 v[130:145], v[222:225], v[230:233], v[130:145]
	v_mfma_f32_32x32x16_bf16 v[234:249], v[226:229], v[230:233], v[234:249]
	ds_read2_b64 v[222:225], v251 offset0:108 offset1:110
	ds_read2_b64 v[226:229], v250 offset0:140 offset1:142
	s_nop 0
	v_cvt_pk_bf16_f32 v230, v82, v83
	v_cvt_pk_bf16_f32 v231, v84, v85
	v_cvt_pk_bf16_f32 v232, v86, v87
	v_cvt_pk_bf16_f32 v233, v88, v89
	s_waitcnt lgkmcnt(2)
	s_nop 1
	v_mfma_f32_32x32x16_bf16 v[130:145], v[194:197], v[230:233], v[130:145]
	v_mfma_f32_32x32x16_bf16 v[234:249], v[218:221], v[230:233], v[234:249]
	ds_read2_b64 v[194:197], v251 offset0:112 offset1:114
	ds_read2_b64 v[218:221], v250 offset0:144 offset1:146
	s_nop 0
	v_cvt_pk_bf16_f32 v230, v90, v91
	v_cvt_pk_bf16_f32 v231, v92, v93
	v_cvt_pk_bf16_f32 v232, v94, v95
	v_cvt_pk_bf16_f32 v233, v96, v97
	s_waitcnt lgkmcnt(2)
	s_nop 1
	v_mfma_f32_32x32x16_bf16 v[130:145], v[222:225], v[230:233], v[130:145]
	v_mfma_f32_32x32x16_bf16 v[234:249], v[226:229], v[230:233], v[234:249]
	ds_read2_b64 v[222:225], v251 offset0:116 offset1:118
	ds_read2_b64 v[226:229], v250 offset0:148 offset1:150
	s_nop 0
	v_cvt_pk_bf16_f32 v230, v98, v99
	v_cvt_pk_bf16_f32 v231, v100, v101
	v_cvt_pk_bf16_f32 v232, v102, v103
	v_cvt_pk_bf16_f32 v233, v104, v105
	s_waitcnt lgkmcnt(2)
	s_nop 1
	v_mfma_f32_32x32x16_bf16 v[130:145], v[194:197], v[230:233], v[130:145]
	v_mfma_f32_32x32x16_bf16 v[234:249], v[218:221], v[230:233], v[234:249]
	ds_read2_b64 v[194:197], v251 offset0:120 offset1:122
	ds_read2_b64 v[218:221], v250 offset0:152 offset1:154
	s_nop 0
	v_cvt_pk_bf16_f32 v230, v106, v107
	v_cvt_pk_bf16_f32 v231, v108, v109
	v_cvt_pk_bf16_f32 v232, v110, v111
	v_cvt_pk_bf16_f32 v233, v112, v113
	s_waitcnt lgkmcnt(2)
	s_nop 1
	v_mfma_f32_32x32x16_bf16 v[130:145], v[222:225], v[230:233], v[130:145]
	v_mfma_f32_32x32x16_bf16 v[234:249], v[226:229], v[230:233], v[234:249]
	ds_read2_b64 v[222:225], v251 offset0:124 offset1:126
	ds_read2_b64 v[226:229], v250 offset0:156 offset1:158
	s_nop 0
	v_cvt_pk_bf16_f32 v230, v114, v115
	v_cvt_pk_bf16_f32 v231, v116, v117
	v_cvt_pk_bf16_f32 v232, v118, v119
	v_cvt_pk_bf16_f32 v233, v120, v121
	s_waitcnt lgkmcnt(2)
	s_nop 1
	v_mfma_f32_32x32x16_bf16 v[130:145], v[194:197], v[230:233], v[130:145]
	v_mfma_f32_32x32x16_bf16 v[234:249], v[218:221], v[230:233], v[234:249]
	s_nop 0
	v_cvt_pk_bf16_f32 v230, v122, v123
	v_cvt_pk_bf16_f32 v231, v124, v125
	v_cvt_pk_bf16_f32 v232, v126, v127
	v_cvt_pk_bf16_f32 v233, v128, v129
	s_waitcnt lgkmcnt(0)
	s_nop 1
	v_mfma_f32_32x32x16_bf16 v[130:145], v[222:225], v[230:233], v[130:145]
	v_mfma_f32_32x32x16_bf16 v[234:249], v[226:229], v[230:233], v[234:249]
	v_fmamk_f32 v193, v192, 0x42800000, v153
	v_exp_f32_e32 v193, v193
	v_or_b32_e32 v194, 0x40000, v172
	v_mov_b32_e32 v195, v173
	v_lshl_add_u64 v[194:195], v[170:171], 0, v[194:195]
	s_nop 6
	v_mul_f32_e32 v130, v193, v130
	v_mov_b32_e32 v251, 0x7fff
	v_bfe_u32 v250, v130, 16, 1
	v_add3_u32 v130, v130, v250, v251
	global_store_short_d16_hi v[194:195], v130, off
	v_fmamk_f32 v130, v192, 0x42820000, v153
	v_exp_f32_e32 v130, v130
	s_nop 0
	v_mul_f32_e32 v130, v130, v131
	v_bfe_u32 v250, v130, 16, 1
	v_add3_u32 v193, v130, v250, v251
	v_or_b32_e32 v130, 0x41000, v172
	v_mov_b32_e32 v131, v173
	v_lshl_add_u64 v[130:131], v[170:171], 0, v[130:131]
	global_store_short_d16_hi v[130:131], v193, off
	v_fmamk_f32 v130, v192, 0x42840000, v153
	v_exp_f32_e32 v130, v130
	v_mov_b32_e32 v131, v173
	v_mul_f32_e32 v130, v130, v132
	v_bfe_u32 v250, v130, 16, 1
	v_add3_u32 v132, v130, v250, v251
	v_or_b32_e32 v130, 0x42000, v172
	v_lshl_add_u64 v[130:131], v[170:171], 0, v[130:131]
	global_store_short_d16_hi v[130:131], v132, off
	v_fmamk_f32 v130, v192, 0x42860000, v153
	v_exp_f32_e32 v130, v130
	v_mov_b32_e32 v131, v173
	v_mul_f32_e32 v130, v130, v133
	v_bfe_u32 v250, v130, 16, 1
	v_add3_u32 v132, v130, v250, v251
	v_or_b32_e32 v130, 0x43000, v172
	v_lshl_add_u64 v[130:131], v[170:171], 0, v[130:131]
	global_store_short_d16_hi v[130:131], v132, off
	v_fmamk_f32 v130, v192, 0x42900000, v153
	v_exp_f32_e32 v130, v130
	v_mov_b32_e32 v131, v173
	v_mul_f32_e32 v130, v130, v134
	v_bfe_u32 v250, v130, 16, 1
	v_add3_u32 v132, v130, v250, v251
	v_or_b32_e32 v130, 0x48000, v172
	v_lshl_add_u64 v[130:131], v[170:171], 0, v[130:131]
	global_store_short_d16_hi v[130:131], v132, off
	v_fmamk_f32 v130, v192, 0x42920000, v153
	v_exp_f32_e32 v130, v130
	v_mov_b32_e32 v131, v173
	v_mul_f32_e32 v130, v130, v135
	v_bfe_u32 v250, v130, 16, 1
	v_add3_u32 v132, v130, v250, v251
	v_or_b32_e32 v130, 0x49000, v172
	v_lshl_add_u64 v[130:131], v[170:171], 0, v[130:131]
	global_store_short_d16_hi v[130:131], v132, off
	v_fmamk_f32 v130, v192, 0x42940000, v153
	v_exp_f32_e32 v130, v130
	v_mov_b32_e32 v131, v173
	v_mul_f32_e32 v130, v130, v136
	v_bfe_u32 v250, v130, 16, 1
	v_add3_u32 v132, v130, v250, v251
	v_or_b32_e32 v130, 0x4a000, v172
	v_lshl_add_u64 v[130:131], v[170:171], 0, v[130:131]
	global_store_short_d16_hi v[130:131], v132, off
	v_fmamk_f32 v130, v192, 0x42960000, v153
	v_exp_f32_e32 v130, v130
	v_mov_b32_e32 v131, v173
	v_mul_f32_e32 v130, v130, v137
	v_bfe_u32 v250, v130, 16, 1
	v_add3_u32 v132, v130, v250, v251
	v_or_b32_e32 v130, 0x4b000, v172
	v_lshl_add_u64 v[130:131], v[170:171], 0, v[130:131]
	global_store_short_d16_hi v[130:131], v132, off
	v_fmamk_f32 v130, v192, 0x42a00000, v153
	v_exp_f32_e32 v130, v130
	v_mov_b32_e32 v131, v173
	v_mul_f32_e32 v130, v130, v138
	v_bfe_u32 v250, v130, 16, 1
	v_add3_u32 v132, v130, v250, v251
	v_or_b32_e32 v130, 0x50000, v172
	v_lshl_add_u64 v[130:131], v[170:171], 0, v[130:131]
	global_store_short_d16_hi v[130:131], v132, off
	v_fmamk_f32 v130, v192, 0x42a20000, v153
	v_exp_f32_e32 v130, v130
	v_mov_b32_e32 v131, v173
	v_mul_f32_e32 v130, v130, v139
	v_bfe_u32 v250, v130, 16, 1
	v_add3_u32 v132, v130, v250, v251
	v_or_b32_e32 v130, 0x51000, v172
	v_lshl_add_u64 v[130:131], v[170:171], 0, v[130:131]
	global_store_short_d16_hi v[130:131], v132, off
	v_fmamk_f32 v130, v192, 0x42a40000, v153
	v_exp_f32_e32 v130, v130
	v_mov_b32_e32 v131, v173
	v_mul_f32_e32 v130, v130, v140
	v_bfe_u32 v250, v130, 16, 1
	v_add3_u32 v132, v130, v250, v251
	v_or_b32_e32 v130, 0x52000, v172
	v_lshl_add_u64 v[130:131], v[170:171], 0, v[130:131]
	global_store_short_d16_hi v[130:131], v132, off
	v_fmamk_f32 v130, v192, 0x42a60000, v153
	v_exp_f32_e32 v130, v130
	v_mov_b32_e32 v131, v173
	v_mul_f32_e32 v130, v130, v141
	v_bfe_u32 v250, v130, 16, 1
	v_add3_u32 v132, v130, v250, v251
	v_or_b32_e32 v130, 0x53000, v172
	v_lshl_add_u64 v[130:131], v[170:171], 0, v[130:131]
	global_store_short_d16_hi v[130:131], v132, off
	v_fmamk_f32 v130, v192, 0x42b00000, v153
	v_exp_f32_e32 v130, v130
	v_mov_b32_e32 v131, v173
	v_mul_f32_e32 v130, v130, v142
	v_bfe_u32 v250, v130, 16, 1
	v_add3_u32 v132, v130, v250, v251
	v_or_b32_e32 v130, 0x58000, v172
	v_lshl_add_u64 v[130:131], v[170:171], 0, v[130:131]
	global_store_short_d16_hi v[130:131], v132, off
	v_fmamk_f32 v130, v192, 0x42b20000, v153
	v_exp_f32_e32 v130, v130
	v_mov_b32_e32 v131, v173
	v_mul_f32_e32 v130, v130, v143
	v_bfe_u32 v250, v130, 16, 1
	v_add3_u32 v132, v130, v250, v251
	v_or_b32_e32 v130, 0x59000, v172
	v_lshl_add_u64 v[130:131], v[170:171], 0, v[130:131]
	global_store_short_d16_hi v[130:131], v132, off
	v_fmamk_f32 v130, v192, 0x42b40000, v153
	v_exp_f32_e32 v130, v130
	v_mov_b32_e32 v131, v173
	v_mul_f32_e32 v130, v130, v144
	v_bfe_u32 v250, v130, 16, 1
	v_add3_u32 v132, v130, v250, v251
	v_or_b32_e32 v130, 0x5a000, v172
	v_lshl_add_u64 v[130:131], v[170:171], 0, v[130:131]
	global_store_short_d16_hi v[130:131], v132, off
	v_fmamk_f32 v130, v192, 0x42b60000, v153
	v_exp_f32_e32 v130, v130
	v_mov_b32_e32 v131, v173
	v_mul_f32_e32 v130, v130, v145
	v_bfe_u32 v250, v130, 16, 1
	v_add3_u32 v132, v130, v250, v251
	v_or_b32_e32 v130, 0x5b000, v172
	v_lshl_add_u64 v[130:131], v[170:171], 0, v[130:131]
	global_store_short_d16_hi v[130:131], v132, off
	v_mov_b32_e32 v130, v234
	v_mov_b32_e32 v131, v235
	v_mov_b32_e32 v132, v236
	v_mov_b32_e32 v133, v237
	v_mov_b32_e32 v134, v238
	v_mov_b32_e32 v135, v239
	v_mov_b32_e32 v136, v240
	v_mov_b32_e32 v137, v241
	v_mov_b32_e32 v138, v242
	v_mov_b32_e32 v139, v243
	v_mov_b32_e32 v140, v244
	v_mov_b32_e32 v141, v245
	v_mov_b32_e32 v142, v246
	v_mov_b32_e32 v143, v247
	v_mov_b32_e32 v144, v248
	v_mov_b32_e32 v145, v249
	v_fmamk_f32 v193, v192, 0x42c00000, v153
	v_exp_f32_e32 v193, v193
	v_or_b32_e32 v194, 0x60000, v172
	v_mov_b32_e32 v195, v173
	v_lshl_add_u64 v[194:195], v[170:171], 0, v[194:195]
	s_nop 6
	v_mul_f32_e32 v130, v193, v130
	v_mov_b32_e32 v251, 0x7fff
	v_bfe_u32 v250, v130, 16, 1
	v_add3_u32 v130, v130, v250, v251
	global_store_short_d16_hi v[194:195], v130, off
	v_fmamk_f32 v130, v192, 0x42c20000, v153
	v_exp_f32_e32 v130, v130
	s_nop 0
	v_mul_f32_e32 v130, v130, v131
	v_bfe_u32 v250, v130, 16, 1
	v_add3_u32 v193, v130, v250, v251
	v_or_b32_e32 v130, 0x61000, v172
	v_mov_b32_e32 v131, v173
	v_lshl_add_u64 v[130:131], v[170:171], 0, v[130:131]
	global_store_short_d16_hi v[130:131], v193, off
	v_fmamk_f32 v130, v192, 0x42c40000, v153
	v_exp_f32_e32 v130, v130
	v_mov_b32_e32 v131, v173
	v_mul_f32_e32 v130, v130, v132
	v_bfe_u32 v250, v130, 16, 1
	v_add3_u32 v132, v130, v250, v251
	v_or_b32_e32 v130, 0x62000, v172
	v_lshl_add_u64 v[130:131], v[170:171], 0, v[130:131]
	global_store_short_d16_hi v[130:131], v132, off
	v_fmamk_f32 v130, v192, 0x42c60000, v153
	v_exp_f32_e32 v130, v130
	v_mov_b32_e32 v131, v173
	v_mul_f32_e32 v130, v130, v133
	v_bfe_u32 v250, v130, 16, 1
	v_add3_u32 v132, v130, v250, v251
	v_or_b32_e32 v130, 0x63000, v172
	v_lshl_add_u64 v[130:131], v[170:171], 0, v[130:131]
	global_store_short_d16_hi v[130:131], v132, off
	v_fmamk_f32 v130, v192, 0x42d00000, v153
	v_exp_f32_e32 v130, v130
	v_mov_b32_e32 v131, v173
	v_mul_f32_e32 v130, v130, v134
	v_bfe_u32 v250, v130, 16, 1
	v_add3_u32 v132, v130, v250, v251
	v_or_b32_e32 v130, 0x68000, v172
	v_lshl_add_u64 v[130:131], v[170:171], 0, v[130:131]
	global_store_short_d16_hi v[130:131], v132, off
	v_fmamk_f32 v130, v192, 0x42d20000, v153
	v_exp_f32_e32 v130, v130
	v_mov_b32_e32 v131, v173
	v_mul_f32_e32 v130, v130, v135
	v_bfe_u32 v250, v130, 16, 1
	v_add3_u32 v132, v130, v250, v251
	v_or_b32_e32 v130, 0x69000, v172
	v_lshl_add_u64 v[130:131], v[170:171], 0, v[130:131]
	global_store_short_d16_hi v[130:131], v132, off
	v_fmamk_f32 v130, v192, 0x42d40000, v153
	v_exp_f32_e32 v130, v130
	v_mov_b32_e32 v131, v173
	v_mul_f32_e32 v130, v130, v136
	v_bfe_u32 v250, v130, 16, 1
	v_add3_u32 v132, v130, v250, v251
	v_or_b32_e32 v130, 0x6a000, v172
	v_lshl_add_u64 v[130:131], v[170:171], 0, v[130:131]
	global_store_short_d16_hi v[130:131], v132, off
	v_fmamk_f32 v130, v192, 0x42d60000, v153
	v_exp_f32_e32 v130, v130
	v_mov_b32_e32 v131, v173
	v_mul_f32_e32 v130, v130, v137
	v_bfe_u32 v250, v130, 16, 1
	v_add3_u32 v132, v130, v250, v251
	v_or_b32_e32 v130, 0x6b000, v172
	v_lshl_add_u64 v[130:131], v[170:171], 0, v[130:131]
	global_store_short_d16_hi v[130:131], v132, off
	v_fmamk_f32 v130, v192, 0x42e00000, v153
	v_exp_f32_e32 v130, v130
	v_mov_b32_e32 v131, v173
	v_mul_f32_e32 v130, v130, v138
	v_bfe_u32 v250, v130, 16, 1
	v_add3_u32 v132, v130, v250, v251
	v_or_b32_e32 v130, 0x70000, v172
	v_lshl_add_u64 v[130:131], v[170:171], 0, v[130:131]
	global_store_short_d16_hi v[130:131], v132, off
	v_fmamk_f32 v130, v192, 0x42e20000, v153
	v_exp_f32_e32 v130, v130
	v_mov_b32_e32 v131, v173
	v_mul_f32_e32 v130, v130, v139
	v_bfe_u32 v250, v130, 16, 1
	v_add3_u32 v132, v130, v250, v251
	v_or_b32_e32 v130, 0x71000, v172
	v_lshl_add_u64 v[130:131], v[170:171], 0, v[130:131]
	global_store_short_d16_hi v[130:131], v132, off
	v_fmamk_f32 v130, v192, 0x42e40000, v153
	v_exp_f32_e32 v130, v130
	v_mov_b32_e32 v131, v173
	v_mul_f32_e32 v130, v130, v140
	v_bfe_u32 v250, v130, 16, 1
	v_add3_u32 v132, v130, v250, v251
	v_or_b32_e32 v130, 0x72000, v172
	v_lshl_add_u64 v[130:131], v[170:171], 0, v[130:131]
	global_store_short_d16_hi v[130:131], v132, off
	v_fmamk_f32 v130, v192, 0x42e60000, v153
	v_exp_f32_e32 v130, v130
	v_mov_b32_e32 v131, v173
	v_mul_f32_e32 v130, v130, v141
	v_bfe_u32 v250, v130, 16, 1
	v_add3_u32 v132, v130, v250, v251
	v_or_b32_e32 v130, 0x73000, v172
	v_lshl_add_u64 v[130:131], v[170:171], 0, v[130:131]
	global_store_short_d16_hi v[130:131], v132, off
	v_fmamk_f32 v130, v192, 0x42f00000, v153
	v_exp_f32_e32 v130, v130
	v_mov_b32_e32 v131, v173
	v_mul_f32_e32 v130, v130, v142
	v_bfe_u32 v250, v130, 16, 1
	v_add3_u32 v132, v130, v250, v251
	v_or_b32_e32 v130, 0x78000, v172
	v_lshl_add_u64 v[130:131], v[170:171], 0, v[130:131]
	global_store_short_d16_hi v[130:131], v132, off
	v_fmamk_f32 v130, v192, 0x42f20000, v153
	v_exp_f32_e32 v130, v130
	v_mov_b32_e32 v131, v173
	v_mul_f32_e32 v130, v130, v143
	v_bfe_u32 v250, v130, 16, 1
	v_add3_u32 v132, v130, v250, v251
	v_or_b32_e32 v130, 0x79000, v172
	v_lshl_add_u64 v[130:131], v[170:171], 0, v[130:131]
	global_store_short_d16_hi v[130:131], v132, off
	v_fmamk_f32 v130, v192, 0x42f40000, v153
	v_exp_f32_e32 v130, v130
	v_mov_b32_e32 v131, v173
	v_fmac_f32_e32 v153, 0x42f60000, v192
	v_mul_f32_e32 v130, v130, v144
	v_bfe_u32 v250, v130, 16, 1
	v_add3_u32 v132, v130, v250, v251
	v_or_b32_e32 v130, 0x7a000, v172
	v_lshl_add_u64 v[130:131], v[170:171], 0, v[130:131]
	global_store_short_d16_hi v[130:131], v132, off
	v_exp_f32_e32 v130, v153
	v_or_b32_e32 v172, 0x7b000, v172
	v_mul_f32_e32 v130, v130, v145
	v_bfe_u32 v250, v130, 16, 1
	v_add3_u32 v132, v130, v250, v251
	v_lshl_add_u64 v[130:131], v[170:171], 0, v[172:173]
	global_store_short_d16_hi v[130:131], v132, off
	v_mov_b32_e32 v153, v189
	s_waitcnt vmcnt(63) expcnt(7) lgkmcnt(15)
	s_barrier
	v_lshl_add_u64 v[132:133], s[64:65], 0, v[164:165]
	v_lshlrev_b64 v[130:131], 1, v[168:169]
	v_lshlrev_b64 v[226:227], 14, v[166:167]
	v_lshl_add_u64 v[226:227], s[64:65], 0, v[226:227]
	v_lshl_add_u64 v[226:227], v[226:227], 0, v[130:131]
	v_mov_b32_e32 v228, v152
	v_mov_b32_e32 v229, v1
	v_lshl_add_u64 v[226:227], v[226:227], 0, v[228:229]
	s_mov_b64 s[6:7], 0xf640000
	v_lshl_add_u64 v[226:227], v[226:227], 0, s[6:7]
	global_load_dwordx4 v[234:237], v[226:227], off
	global_load_dwordx4 v[238:241], v[226:227], off offset:32
	global_load_dwordx4 v[242:245], v[226:227], off offset:64
	global_load_dwordx4 v[246:249], v[226:227], off offset:96
	v_lshl_add_u64 v[132:133], v[132:133], 0, v[130:131]
	v_lshlrev_b32_e32 v134, 4, v153
	v_and_b32_e32 v144, 0xf0, v134
	v_mov_b32_e32 v145, v1
	v_lshlrev_b32_e32 v134, 10, v153
	v_lshl_add_u64 v[132:133], v[132:133], 0, v[144:145]
	v_and_b32_e32 v134, 0x3c000, v134
	v_mov_b32_e32 v135, v1
	v_lshl_add_u64 v[172:173], v[132:133], 0, v[134:135]
	s_mov_b32 s6, 0xe640000
	v_add_co_u32_e64 v132, s[6:7], s6, v172
	v_bfe_u32 v145, v153, 4, 4
	s_nop 0
	v_addc_co_u32_e64 v133, s[6:7], 0, v173, s[6:7]
	s_mov_b32 s6, 0xe680000
	s_nop 0
	v_add_co_u32_e64 v136, s[6:7], s6, v172
	global_load_dwordx4 v[132:135], v[132:133], off
	s_nop 0
	v_addc_co_u32_e64 v137, s[6:7], 0, v173, s[6:7]
	s_mov_b32 s6, 0xe6c0000
	s_nop 0
	v_add_co_u32_e64 v140, s[6:7], s6, v172
	global_load_dwordx4 v[136:139], v[136:137], off
	s_nop 0
	v_addc_co_u32_e64 v141, s[6:7], 0, v173, s[6:7]
	s_mov_b32 s6, 0xe700000
	s_nop 0
	v_add_co_u32_e64 v168, s[6:7], s6, v172
	global_load_dwordx4 v[140:143], v[140:141], off
	s_nop 0
	v_addc_co_u32_e64 v169, s[6:7], 0, v173, s[6:7]
	s_mov_b32 s6, 0xe740000
	s_nop 0
	v_add_co_u32_e64 v192, s[6:7], s6, v172
	global_load_dwordx4 v[168:171], v[168:169], off
	s_nop 0
	v_addc_co_u32_e64 v193, s[6:7], 0, v173, s[6:7]
	s_mov_b32 s6, 0xe780000
	s_nop 0
	v_add_co_u32_e64 v196, s[6:7], s6, v172
	global_load_dwordx4 v[192:195], v[192:193], off
	s_nop 0
	v_addc_co_u32_e64 v197, s[6:7], 0, v173, s[6:7]
	s_mov_b32 s6, 0xe7c0000
	s_nop 0
	v_add_co_u32_e64 v208, s[6:7], s6, v172
	global_load_dwordx4 v[196:199], v[196:197], off
	s_nop 0
	v_addc_co_u32_e64 v209, s[6:7], 0, v173, s[6:7]
	s_mov_b32 s6, 0xe800000
	global_load_dwordx4 v[218:221], v[208:209], off
	v_add_co_u32_e64 v208, s[6:7], s6, v172
	v_mul_u32_u24_e32 v145, 0x108, v145
	s_nop 0
	v_addc_co_u32_e64 v209, s[6:7], 0, v173, s[6:7]
	global_load_dwordx4 v[222:225], v[208:209], off
	v_add3_u32 v153, v149, v144, v145
	s_waitcnt vmcnt(7)
	ds_write2_b64 v153, v[132:133], v[134:135] offset1:1
	v_add_u32_e32 v132, 0x1080, v153
	s_waitcnt vmcnt(6)
	ds_write2_b64 v132, v[136:137], v[138:139] offset1:1
	v_add_u32_e32 v132, 0x2100, v153
	s_waitcnt vmcnt(5)
	ds_write2_b64 v132, v[140:141], v[142:143] offset1:1
	v_add_u32_e32 v132, 0x3180, v153
	s_waitcnt vmcnt(4)
	ds_write2_b64 v132, v[168:169], v[170:171] offset1:1
	v_add_u32_e32 v132, 0x4200, v153
	s_waitcnt vmcnt(3)
	ds_write2_b64 v132, v[192:193], v[194:195] offset1:1
	v_add_u32_e32 v132, 0x5280, v153
	s_waitcnt vmcnt(2)
	ds_write2_b64 v132, v[196:197], v[198:199] offset1:1
	v_add_u32_e32 v132, 0x6300, v153
	s_waitcnt vmcnt(1)
	ds_write2_b64 v132, v[218:219], v[220:221] offset1:1
	v_add_u32_e32 v132, 0x7380, v153
	s_waitcnt vmcnt(0)
	ds_write2_b64 v132, v[222:223], v[224:225] offset1:1
	s_mov_b32 s6, 0xe840000
	v_add_co_u32_e64 v132, s[6:7], s6, v172
	s_nop 1
	v_addc_co_u32_e64 v133, s[6:7], 0, v173, s[6:7]
	s_mov_b32 s6, 0xe880000
	s_nop 0
	v_add_co_u32_e64 v136, s[6:7], s6, v172
	global_load_dwordx4 v[132:135], v[132:133], off
	s_nop 0
	v_addc_co_u32_e64 v137, s[6:7], 0, v173, s[6:7]
	s_mov_b32 s6, 0xe8c0000
	s_nop 0
	v_add_co_u32_e64 v140, s[6:7], s6, v172
	global_load_dwordx4 v[136:139], v[136:137], off
	s_nop 0
	v_addc_co_u32_e64 v141, s[6:7], 0, v173, s[6:7]
	s_mov_b32 s6, 0xe900000
	s_nop 0
	v_add_co_u32_e64 v144, s[6:7], s6, v172
	global_load_dwordx4 v[140:143], v[140:141], off
	s_nop 0
	v_addc_co_u32_e64 v145, s[6:7], 0, v173, s[6:7]
	s_mov_b32 s6, 0xe940000
	global_load_dwordx4 v[168:171], v[144:145], off
	v_add_co_u32_e64 v144, s[6:7], s6, v172
	s_nop 1
	v_addc_co_u32_e64 v145, s[6:7], 0, v173, s[6:7]
	s_mov_b32 s6, 0xe980000
	global_load_dwordx4 v[192:195], v[144:145], off
	v_add_co_u32_e64 v144, s[6:7], s6, v172
	s_nop 1
	v_addc_co_u32_e64 v145, s[6:7], 0, v173, s[6:7]
	s_mov_b32 s6, 0xe9c0000
	global_load_dwordx4 v[196:199], v[144:145], off
	v_add_co_u32_e64 v144, s[6:7], s6, v172
	s_nop 1
	v_addc_co_u32_e64 v145, s[6:7], 0, v173, s[6:7]
	s_mov_b32 s6, 0xea00000
	global_load_dwordx4 v[218:221], v[144:145], off
	v_add_co_u32_e64 v144, s[6:7], s6, v172
	s_nop 1
	v_addc_co_u32_e64 v145, s[6:7], 0, v173, s[6:7]
	global_load_dwordx4 v[222:225], v[144:145], off
	v_add_u32_e32 v144, 0x8400, v153
	s_waitcnt vmcnt(7)
	ds_write2_b64 v144, v[132:133], v[134:135] offset1:1
	v_add_u32_e32 v132, 0x9480, v153
	s_waitcnt vmcnt(6)
	ds_write2_b64 v132, v[136:137], v[138:139] offset1:1
	v_add_u32_e32 v132, 0xa500, v153
	s_waitcnt vmcnt(5)
	ds_write2_b64 v132, v[140:141], v[142:143] offset1:1
	v_add_u32_e32 v132, 0xb580, v153
	s_waitcnt vmcnt(4)
	ds_write2_b64 v132, v[168:169], v[170:171] offset1:1
	v_add_u32_e32 v132, 0xc600, v153
	s_waitcnt vmcnt(3)
	ds_write2_b64 v132, v[192:193], v[194:195] offset1:1
	v_add_u32_e32 v132, 0xd680, v153
	s_waitcnt vmcnt(2)
	ds_write2_b64 v132, v[196:197], v[198:199] offset1:1
	v_add_u32_e32 v132, 0xe700, v153
	s_waitcnt vmcnt(1)
	ds_write2_b64 v132, v[218:219], v[220:221] offset1:1
	v_add_u32_e32 v132, 0xf780, v153
	s_waitcnt vmcnt(0)
	ds_write2_b64 v132, v[222:223], v[224:225] offset1:1
	s_waitcnt lgkmcnt(0)
	s_barrier
	v_lshlrev_b64 v[132:133], 14, v[166:167]
	v_lshl_add_u64 v[132:133], s[64:65], 0, v[132:133]
	v_lshl_add_u64 v[130:131], v[132:133], 0, v[130:131]
	v_mov_b32_e32 v153, v1
	v_lshl_add_u64 v[134:135], v[130:131], 0, v[152:153]
	s_mov_b32 s6, 0xf640000
	v_add_co_u32_e64 v130, s[6:7], s6, v134
	v_mul_f32 v2, v2, v159
	v_mul_f32 v3, v3, v159
	v_mul_f32 v4, v4, v159
	v_mul_f32 v5, v5, v159
	s_nop 1
	v_addc_co_u32_e64 v131, s[6:7], 0, v135, s[6:7]
	v_mul_f32 v6, v6, v159
	v_mul_f32 v7, v7, v159
	v_mul_f32 v8, v8, v159
	v_mul_f32 v9, v9, v159
	v_mul_f32 v10, v10, v159
	v_mul_f32 v11, v11, v159
	v_mul_f32 v12, v12, v159
	v_mul_f32 v13, v13, v159
	v_mul_f32 v14, v14, v159
	v_mul_f32 v15, v15, v159
	v_mul_f32 v16, v16, v159
	v_mul_f32 v17, v17, v159
	v_mul_f32 v18, v18, v159
	v_mul_f32 v19, v19, v159
	v_mul_f32 v20, v20, v159
	v_mul_f32 v21, v21, v159
	v_mul_f32 v22, v22, v159
	v_mul_f32 v23, v23, v159
	v_mul_f32 v24, v24, v159
	v_mul_f32 v25, v25, v159
	v_mul_f32 v26, v26, v159
	v_mul_f32 v27, v27, v159
	v_mul_f32 v28, v28, v159
	v_mul_f32 v29, v29, v159
	v_mul_f32 v30, v30, v159
	v_mul_f32 v31, v31, v159
	v_mul_f32 v32, v32, v159
	v_mul_f32 v33, v33, v159
	v_mul_f32 v34, v34, v159
	v_mul_f32 v35, v35, v159
	v_mul_f32 v36, v36, v159
	v_mul_f32 v37, v37, v159
	v_mul_f32 v38, v38, v159
	v_mul_f32 v39, v39, v159
	v_mul_f32 v40, v40, v159
	v_mul_f32 v41, v41, v159
	v_mul_f32 v42, v42, v159
	v_mul_f32 v43, v43, v159
	v_mul_f32 v44, v44, v159
	v_mul_f32 v45, v45, v159
	v_mul_f32 v46, v46, v159
	v_mul_f32 v47, v47, v159
	v_mul_f32 v48, v48, v159
	v_mul_f32 v49, v49, v159
	v_mul_f32 v50, v50, v159
	v_mul_f32 v51, v51, v159
	v_mul_f32 v52, v52, v159
	v_mul_f32 v53, v53, v159
	v_mul_f32 v54, v54, v159
	v_mul_f32 v55, v55, v159
	v_mul_f32 v56, v56, v159
	v_mul_f32 v57, v57, v159
	v_mul_f32 v58, v58, v159
	v_mul_f32 v59, v59, v159
	v_mul_f32 v60, v60, v159
	v_mul_f32 v61, v61, v159
	v_mul_f32 v62, v62, v159
	v_mul_f32 v63, v63, v159
	v_mul_f32 v64, v64, v159
	v_mul_f32 v65, v65, v159
	v_mul_f32 v66, v66, v159
	v_mul_f32 v67, v67, v159
	v_mul_f32 v68, v68, v159
	v_mul_f32 v69, v69, v159
	v_mul_f32 v70, v70, v159
	v_mul_f32 v71, v71, v159
	v_mul_f32 v72, v72, v159
	v_mul_f32 v73, v73, v159
	v_mul_f32 v74, v74, v159
	v_mul_f32 v75, v75, v159
	v_mul_f32 v76, v76, v159
	v_mul_f32 v77, v77, v159
	v_mul_f32 v78, v78, v159
	v_mul_f32 v79, v79, v159
	v_mul_f32 v80, v80, v159
	v_mul_f32 v81, v81, v159
	v_mul_f32 v82, v82, v159
	v_mul_f32 v83, v83, v159
	v_mul_f32 v84, v84, v159
	v_mul_f32 v85, v85, v159
	v_mul_f32 v86, v86, v159
	v_mul_f32 v87, v87, v159
	v_mul_f32 v88, v88, v159
	v_mul_f32 v89, v89, v159
	v_mul_f32 v90, v90, v159
	v_mul_f32 v91, v91, v159
	v_mul_f32 v92, v92, v159
	v_mul_f32 v93, v93, v159
	v_mul_f32 v94, v94, v159
	v_mul_f32 v95, v95, v159
	v_mul_f32 v96, v96, v159
	v_mul_f32 v97, v97, v159
	v_mul_f32 v98, v98, v159
	v_mul_f32 v99, v99, v159
	v_mul_f32 v100, v100, v159
	v_mul_f32 v101, v101, v159
	v_mul_f32 v102, v102, v159
	v_mul_f32 v103, v103, v159
	v_mul_f32 v104, v104, v159
	v_mul_f32 v105, v105, v159
	v_mul_f32 v106, v106, v159
	v_mul_f32 v107, v107, v159
	v_mul_f32 v108, v108, v159
	v_mul_f32 v109, v109, v159
	v_mul_f32 v110, v110, v159
	v_mul_f32 v111, v111, v159
	v_mul_f32 v112, v112, v159
	v_mul_f32 v113, v113, v159
	v_mul_f32 v114, v114, v159
	v_mul_f32 v115, v115, v159
	v_mul_f32 v116, v116, v159
	v_mul_f32 v117, v117, v159
	v_mul_f32 v118, v118, v159
	v_mul_f32 v119, v119, v159
	v_mul_f32 v120, v120, v159
	v_mul_f32 v121, v121, v159
	v_mul_f32 v122, v122, v159
	v_mul_f32 v123, v123, v159
	v_mul_f32 v124, v124, v159
	v_mul_f32 v125, v125, v159
	v_mul_f32 v126, v126, v159
	v_mul_f32 v127, v127, v159
	v_mul_f32 v128, v128, v159
	v_mul_f32 v129, v129, v159
	s_mov_b64 s[6:7], 0xf640000
	v_lshl_add_u64 v[142:143], v[134:135], 0, s[6:7]
	v_mov_b32_e32 v130, v234
	v_mov_b32_e32 v131, v235
	v_mov_b32_e32 v132, v236
	v_mov_b32_e32 v133, v237
	v_mov_b32_e32 v134, v238
	v_mov_b32_e32 v135, v239
	v_mov_b32_e32 v136, v240
	v_mov_b32_e32 v137, v241
	v_mov_b32_e32 v138, v242
	v_mov_b32_e32 v139, v243
	v_mov_b32_e32 v140, v244
	v_mov_b32_e32 v141, v245
	v_mov_b32_e32 v166, v246
	v_mov_b32_e32 v167, v247
	v_mov_b32_e32 v168, v248
	v_mov_b32_e32 v169, v249
	global_load_dwordx4 v[234:237], v[142:143], off offset:128
	global_load_dwordx4 v[238:241], v[142:143], off offset:160
	global_load_dwordx4 v[242:245], v[142:143], off offset:192
	global_load_dwordx4 v[246:249], v[142:143], off offset:224
	v_fma_f32 v144, 0, v191, v190
	v_add_f32_e32 v145, v190, v191
	v_exp_f32_e32 v144, v144
	v_exp_f32_e32 v145, v145
	v_fmamk_f32 v153, v191, 0x42480000, v190
	s_waitcnt vmcnt(4)
	v_lshlrev_b32_e32 v170, 16, v130
	v_and_b32_e32 v171, 0xffff0000, v130
	v_fma_f32 v130, 2.0, v191, v190
	v_pk_mul_f32 v[144:145], v[144:145], v[170:171]
	v_exp_f32_e32 v170, v130
	v_fmamk_f32 v130, v191, 0x40400000, v190
	v_exp_f32_e32 v171, v130
	v_cvt_pk_bf16_f32 v130, v144, v145
	v_lshlrev_b32_e32 v144, 16, v131
	v_and_b32_e32 v145, 0xffff0000, v131
	v_fma_f32 v131, 4.0, v191, v190
	v_pk_mul_f32 v[144:145], v[170:171], v[144:145]
	v_exp_f32_e32 v170, v131
	v_fmamk_f32 v131, v191, 0x40a00000, v190
	v_exp_f32_e32 v171, v131
	v_cvt_pk_bf16_f32 v131, v144, v145
	v_lshlrev_b32_e32 v144, 16, v132
	v_and_b32_e32 v145, 0xffff0000, v132
	v_fmamk_f32 v132, v191, 0x40c00000, v190
	v_pk_mul_f32 v[144:145], v[170:171], v[144:145]
	v_exp_f32_e32 v170, v132
	v_fmamk_f32 v132, v191, 0x40e00000, v190
	v_exp_f32_e32 v171, v132
	v_cvt_pk_bf16_f32 v132, v144, v145
	v_lshlrev_b32_e32 v144, 16, v133
	v_and_b32_e32 v145, 0xffff0000, v133
	v_fmamk_f32 v133, v191, 0x41800000, v190
	v_pk_mul_f32 v[144:145], v[170:171], v[144:145]
	v_exp_f32_e32 v170, v133
	v_fmamk_f32 v133, v191, 0x41880000, v190
	v_exp_f32_e32 v171, v133
	v_cvt_pk_bf16_f32 v133, v144, v145
	s_waitcnt vmcnt(4)
	v_lshlrev_b32_e32 v144, 16, v134
	v_and_b32_e32 v145, 0xffff0000, v134
	v_fmamk_f32 v134, v191, 0x41900000, v190
	v_pk_mul_f32 v[144:145], v[170:171], v[144:145]
	v_exp_f32_e32 v170, v134
	v_fmamk_f32 v134, v191, 0x41980000, v190
	v_exp_f32_e32 v171, v134
	v_cvt_pk_bf16_f32 v134, v144, v145
	v_lshlrev_b32_e32 v144, 16, v135
	v_and_b32_e32 v145, 0xffff0000, v135
	v_fmamk_f32 v135, v191, 0x41a00000, v190
	v_pk_mul_f32 v[144:145], v[170:171], v[144:145]
	v_exp_f32_e32 v170, v135
	v_fmamk_f32 v135, v191, 0x41a80000, v190
	v_exp_f32_e32 v171, v135
	v_cvt_pk_bf16_f32 v135, v144, v145
	v_lshlrev_b32_e32 v144, 16, v136
	v_and_b32_e32 v145, 0xffff0000, v136
	v_fmamk_f32 v136, v191, 0x41b00000, v190
	v_pk_mul_f32 v[144:145], v[170:171], v[144:145]
	v_exp_f32_e32 v170, v136
	v_fmamk_f32 v136, v191, 0x41b80000, v190
	v_exp_f32_e32 v171, v136
	v_cvt_pk_bf16_f32 v136, v144, v145
	v_lshlrev_b32_e32 v144, 16, v137
	v_and_b32_e32 v145, 0xffff0000, v137
	v_fmamk_f32 v137, v191, 0x42000000, v190
	v_pk_mul_f32 v[144:145], v[170:171], v[144:145]
	v_exp_f32_e32 v170, v137
	v_fmamk_f32 v137, v191, 0x42040000, v190
	v_exp_f32_e32 v171, v137
	v_cvt_pk_bf16_f32 v137, v144, v145
	s_waitcnt vmcnt(4)
	v_lshlrev_b32_e32 v144, 16, v138
	v_and_b32_e32 v145, 0xffff0000, v138
	v_fmamk_f32 v138, v191, 0x42080000, v190
	v_pk_mul_f32 v[144:145], v[170:171], v[144:145]
	v_exp_f32_e32 v170, v138
	v_fmamk_f32 v138, v191, 0x420c0000, v190
	v_exp_f32_e32 v171, v138
	v_cvt_pk_bf16_f32 v138, v144, v145
	v_lshlrev_b32_e32 v144, 16, v139
	v_and_b32_e32 v145, 0xffff0000, v139
	v_fmamk_f32 v139, v191, 0x42100000, v190
	v_pk_mul_f32 v[144:145], v[170:171], v[144:145]
	v_exp_f32_e32 v170, v139
	v_fmamk_f32 v139, v191, 0x42140000, v190
	v_exp_f32_e32 v171, v139
	v_cvt_pk_bf16_f32 v139, v144, v145
	v_lshlrev_b32_e32 v144, 16, v140
	v_and_b32_e32 v145, 0xffff0000, v140
	v_fmamk_f32 v140, v191, 0x42180000, v190
	v_pk_mul_f32 v[144:145], v[170:171], v[144:145]
	v_exp_f32_e32 v170, v140
	v_fmamk_f32 v140, v191, 0x421c0000, v190
	v_exp_f32_e32 v171, v140
	v_cvt_pk_bf16_f32 v140, v144, v145
	v_lshlrev_b32_e32 v144, 16, v141
	v_and_b32_e32 v145, 0xffff0000, v141
	v_fmamk_f32 v141, v191, 0x42400000, v190
	v_pk_mul_f32 v[144:145], v[170:171], v[144:145]
	v_exp_f32_e32 v170, v141
	v_fmamk_f32 v141, v191, 0x42440000, v190
	v_exp_f32_e32 v171, v141
	v_cvt_pk_bf16_f32 v141, v144, v145
	s_waitcnt vmcnt(4)
	v_lshlrev_b32_e32 v144, 16, v166
	v_and_b32_e32 v145, 0xffff0000, v166
	v_pk_mul_f32 v[144:145], v[170:171], v[144:145]
	v_exp_f32_e32 v170, v153
	v_fmamk_f32 v153, v191, 0x424c0000, v190
	v_exp_f32_e32 v171, v153
	v_cvt_pk_bf16_f32 v166, v144, v145
	v_lshlrev_b32_e32 v144, 16, v167
	v_and_b32_e32 v145, 0xffff0000, v167
	v_fmamk_f32 v153, v191, 0x42500000, v190
	v_pk_mul_f32 v[144:145], v[170:171], v[144:145]
	v_exp_f32_e32 v170, v153
	v_fmamk_f32 v153, v191, 0x42540000, v190
	v_exp_f32_e32 v171, v153
	v_cvt_pk_bf16_f32 v167, v144, v145
	v_lshlrev_b32_e32 v144, 16, v168
	v_and_b32_e32 v145, 0xffff0000, v168
	v_fmamk_f32 v153, v191, 0x42580000, v190
	v_pk_mul_f32 v[144:145], v[170:171], v[144:145]
	v_exp_f32_e32 v170, v153
	v_fmamk_f32 v153, v191, 0x425c0000, v190
	v_exp_f32_e32 v171, v153
	v_cvt_pk_bf16_f32 v168, v144, v145
	v_lshlrev_b32_e32 v144, 16, v169
	v_and_b32_e32 v145, 0xffff0000, v169
	v_pk_mul_f32 v[144:145], v[170:171], v[144:145]
	s_nop 0
	v_cvt_pk_bf16_f32 v169, v144, v145
	ds_read2_b64 v[170:173], v179 offset1:1
	ds_read2_b64 v[192:195], v179 offset0:4 offset1:5
	ds_read2_b64 v[196:199], v179 offset0:8 offset1:9
	ds_read2_b64 v[218:221], v179 offset0:12 offset1:13
	s_waitcnt lgkmcnt(3)
	v_mfma_f32_32x32x16_bf16 v[2:17], v[170:173], v[130:133], v[2:17]
	v_add_u32_e32 v144, 0x2100, v179
	ds_read2_b64 v[170:173], v144 offset1:1
	s_waitcnt lgkmcnt(3)
	v_mfma_f32_32x32x16_bf16 v[2:17], v[192:195], v[134:137], v[2:17]
	v_add_u32_e32 v144, 0x2120, v179
	ds_read2_b64 v[192:195], v144 offset1:1
	s_waitcnt lgkmcnt(3)
	v_mfma_f32_32x32x16_bf16 v[2:17], v[196:199], v[138:141], v[2:17]
	v_add_u32_e32 v144, 0x2140, v179
	ds_read2_b64 v[196:199], v144 offset1:1
	s_waitcnt lgkmcnt(3)
	v_mfma_f32_32x32x16_bf16 v[2:17], v[218:221], v[166:169], v[2:17]
	v_add_u32_e32 v144, 0x2160, v179
	ds_read2_b64 v[218:221], v144 offset1:1
	s_waitcnt lgkmcnt(3)
	v_mfma_f32_32x32x16_bf16 v[18:33], v[170:173], v[130:133], v[18:33]
	v_add_u32_e32 v144, 0x4200, v179
	ds_read2_b64 v[170:173], v144 offset1:1
	s_waitcnt lgkmcnt(3)
	v_mfma_f32_32x32x16_bf16 v[18:33], v[192:195], v[134:137], v[18:33]
	v_add_u32_e32 v144, 0x4220, v179
	ds_read2_b64 v[192:195], v144 offset1:1
	s_waitcnt lgkmcnt(3)
	v_mfma_f32_32x32x16_bf16 v[18:33], v[196:199], v[138:141], v[18:33]
	v_add_u32_e32 v144, 0x4240, v179
	ds_read2_b64 v[196:199], v144 offset1:1
	s_waitcnt lgkmcnt(3)
	v_mfma_f32_32x32x16_bf16 v[18:33], v[218:221], v[166:169], v[18:33]
	v_add_u32_e32 v144, 0x4260, v179
	ds_read2_b64 v[218:221], v144 offset1:1
	s_waitcnt lgkmcnt(3)
	v_mfma_f32_32x32x16_bf16 v[34:49], v[170:173], v[130:133], v[34:49]
	v_add_u32_e32 v144, 0x6300, v179
	ds_read2_b64 v[170:173], v144 offset1:1
	s_waitcnt lgkmcnt(3)
	v_mfma_f32_32x32x16_bf16 v[34:49], v[192:195], v[134:137], v[34:49]
	v_add_u32_e32 v144, 0x6320, v179
	ds_read2_b64 v[192:195], v144 offset1:1
	s_waitcnt lgkmcnt(3)
	v_mfma_f32_32x32x16_bf16 v[34:49], v[196:199], v[138:141], v[34:49]
	v_add_u32_e32 v144, 0x6340, v179
	ds_read2_b64 v[196:199], v144 offset1:1
	s_waitcnt lgkmcnt(3)
	v_mfma_f32_32x32x16_bf16 v[34:49], v[218:221], v[166:169], v[34:49]
	v_add_u32_e32 v144, 0x6360, v179
	ds_read2_b64 v[218:221], v144 offset1:1
	s_waitcnt lgkmcnt(3)
	v_mfma_f32_32x32x16_bf16 v[50:65], v[170:173], v[130:133], v[50:65]
	v_add_u32_e32 v144, 0x8400, v179
	ds_read2_b64 v[170:173], v144 offset1:1
	s_waitcnt lgkmcnt(3)
	v_mfma_f32_32x32x16_bf16 v[50:65], v[192:195], v[134:137], v[50:65]
	v_add_u32_e32 v144, 0x8420, v179
	ds_read2_b64 v[192:195], v144 offset1:1
	s_waitcnt lgkmcnt(3)
	v_mfma_f32_32x32x16_bf16 v[50:65], v[196:199], v[138:141], v[50:65]
	v_add_u32_e32 v144, 0x8440, v179
	ds_read2_b64 v[196:199], v144 offset1:1
	s_waitcnt lgkmcnt(3)
	v_mfma_f32_32x32x16_bf16 v[50:65], v[218:221], v[166:169], v[50:65]
	v_add_u32_e32 v144, 0x8460, v179
	ds_read2_b64 v[218:221], v144 offset1:1
	s_waitcnt lgkmcnt(3)
	v_mfma_f32_32x32x16_bf16 v[66:81], v[170:173], v[130:133], v[66:81]
	v_add_u32_e32 v144, 0xa500, v179
	ds_read2_b64 v[170:173], v144 offset1:1
	s_waitcnt lgkmcnt(3)
	v_mfma_f32_32x32x16_bf16 v[66:81], v[192:195], v[134:137], v[66:81]
	v_add_u32_e32 v144, 0xa520, v179
	ds_read2_b64 v[192:195], v144 offset1:1
	s_waitcnt lgkmcnt(3)
	v_mfma_f32_32x32x16_bf16 v[66:81], v[196:199], v[138:141], v[66:81]
	v_add_u32_e32 v144, 0xa540, v179
	ds_read2_b64 v[196:199], v144 offset1:1
	s_waitcnt lgkmcnt(3)
	v_mfma_f32_32x32x16_bf16 v[66:81], v[218:221], v[166:169], v[66:81]
	v_add_u32_e32 v144, 0xa560, v179
	ds_read2_b64 v[218:221], v144 offset1:1
	s_waitcnt lgkmcnt(3)
	v_mfma_f32_32x32x16_bf16 v[82:97], v[170:173], v[130:133], v[82:97]
	v_add_u32_e32 v144, 0xc600, v179
	ds_read2_b64 v[170:173], v144 offset1:1
	s_waitcnt lgkmcnt(3)
	v_mfma_f32_32x32x16_bf16 v[82:97], v[192:195], v[134:137], v[82:97]
	v_add_u32_e32 v144, 0xc620, v179
	ds_read2_b64 v[192:195], v144 offset1:1
	s_waitcnt lgkmcnt(3)
	v_mfma_f32_32x32x16_bf16 v[82:97], v[196:199], v[138:141], v[82:97]
	v_add_u32_e32 v144, 0xc640, v179
	ds_read2_b64 v[196:199], v144 offset1:1
	s_waitcnt lgkmcnt(3)
	v_mfma_f32_32x32x16_bf16 v[82:97], v[218:221], v[166:169], v[82:97]
	v_add_u32_e32 v144, 0xc660, v179
	ds_read2_b64 v[218:221], v144 offset1:1
	s_waitcnt lgkmcnt(3)
	v_mfma_f32_32x32x16_bf16 v[98:113], v[170:173], v[130:133], v[98:113]
	v_add_u32_e32 v144, 0xe700, v179
	ds_read2_b64 v[170:173], v144 offset1:1
	s_waitcnt lgkmcnt(3)
	v_mfma_f32_32x32x16_bf16 v[98:113], v[192:195], v[134:137], v[98:113]
	v_add_u32_e32 v144, 0xe720, v179
	ds_read2_b64 v[192:195], v144 offset1:1
	s_waitcnt lgkmcnt(3)
	v_mfma_f32_32x32x16_bf16 v[98:113], v[196:199], v[138:141], v[98:113]
	v_add_u32_e32 v144, 0xe740, v179
	ds_read2_b64 v[196:199], v144 offset1:1
	s_waitcnt lgkmcnt(3)
	v_mfma_f32_32x32x16_bf16 v[98:113], v[218:221], v[166:169], v[98:113]
	v_add_u32_e32 v144, 0xe760, v179
	ds_read2_b64 v[218:221], v144 offset1:1
	s_waitcnt lgkmcnt(3)
	v_mfma_f32_32x32x16_bf16 v[114:129], v[170:173], v[130:133], v[114:129]
	s_waitcnt lgkmcnt(2)
	v_mfma_f32_32x32x16_bf16 v[114:129], v[192:195], v[134:137], v[114:129]
	s_waitcnt lgkmcnt(1)
	v_mfma_f32_32x32x16_bf16 v[114:129], v[196:199], v[138:141], v[114:129]
	s_waitcnt lgkmcnt(0)
	v_mfma_f32_32x32x16_bf16 v[114:129], v[218:221], v[166:169], v[114:129]
	v_fmamk_f32 v134, v191, 0x42800000, v190
	v_fmamk_f32 v135, v191, 0x42820000, v190
	v_exp_f32_e32 v134, v134
	v_exp_f32_e32 v135, v135
	v_fmamk_f32 v138, v191, 0x42a00000, v190
	v_fmamk_f32 v139, v191, 0x42a20000, v190
	v_exp_f32_e32 v138, v138
	v_exp_f32_e32 v139, v139
	v_fmamk_f32 v144, v191, 0x42c00000, v190
	v_fmamk_f32 v145, v191, 0x42c20000, v190
	v_exp_f32_e32 v144, v144
	v_exp_f32_e32 v145, v145
	v_fmamk_f32 v153, v191, 0x42e00000, v190
	s_waitcnt vmcnt(0)
	v_mov_b32_e32 v130, v234
	v_mov_b32_e32 v131, v235
	v_mov_b32_e32 v132, v236
	v_mov_b32_e32 v133, v237
	v_lshlrev_b32_e32 v136, 16, v130
	v_and_b32_e32 v137, 0xffff0000, v130
	v_pk_mul_f32 v[134:135], v[134:135], v[136:137]
	v_lshlrev_b32_e32 v136, 16, v131
	v_cvt_pk_bf16_f32 v130, v134, v135
	v_fmamk_f32 v134, v191, 0x42840000, v190
	v_fmamk_f32 v135, v191, 0x42860000, v190
	v_exp_f32_e32 v134, v134
	v_exp_f32_e32 v135, v135
	v_and_b32_e32 v137, 0xffff0000, v131
	v_pk_mul_f32 v[134:135], v[134:135], v[136:137]
	s_nop 0
	v_cvt_pk_bf16_f32 v131, v134, v135
	v_fmamk_f32 v134, v191, 0x42880000, v190
	v_fmamk_f32 v135, v191, 0x428a0000, v190
	v_exp_f32_e32 v134, v134
	v_exp_f32_e32 v135, v135
	v_lshlrev_b32_e32 v136, 16, v132
	v_and_b32_e32 v137, 0xffff0000, v132
	v_pk_mul_f32 v[134:135], v[134:135], v[136:137]
	s_nop 0
	v_cvt_pk_bf16_f32 v132, v134, v135
	v_fmamk_f32 v134, v191, 0x428c0000, v190
	v_fmamk_f32 v135, v191, 0x428e0000, v190
	v_exp_f32_e32 v134, v134
	v_exp_f32_e32 v135, v135
	v_lshlrev_b32_e32 v136, 16, v133
	v_and_b32_e32 v137, 0xffff0000, v133
	v_pk_mul_f32 v[134:135], v[134:135], v[136:137]
	s_nop 0
	v_cvt_pk_bf16_f32 v133, v134, v135
	s_waitcnt vmcnt(0)
	v_mov_b32_e32 v134, v238
	v_mov_b32_e32 v135, v239
	v_mov_b32_e32 v136, v240
	v_mov_b32_e32 v137, v241
	v_lshlrev_b32_e32 v140, 16, v134
	v_and_b32_e32 v141, 0xffff0000, v134
	v_pk_mul_f32 v[138:139], v[138:139], v[140:141]
	v_lshlrev_b32_e32 v140, 16, v135
	v_cvt_pk_bf16_f32 v134, v138, v139
	v_fmamk_f32 v138, v191, 0x42a40000, v190
	v_fmamk_f32 v139, v191, 0x42a60000, v190
	v_exp_f32_e32 v138, v138
	v_exp_f32_e32 v139, v139
	v_and_b32_e32 v141, 0xffff0000, v135
	v_pk_mul_f32 v[138:139], v[138:139], v[140:141]
	s_nop 0
	v_cvt_pk_bf16_f32 v135, v138, v139
	v_fmamk_f32 v138, v191, 0x42a80000, v190
	v_fmamk_f32 v139, v191, 0x42aa0000, v190
	v_exp_f32_e32 v138, v138
	v_exp_f32_e32 v139, v139
	v_lshlrev_b32_e32 v140, 16, v136
	v_and_b32_e32 v141, 0xffff0000, v136
	v_pk_mul_f32 v[138:139], v[138:139], v[140:141]
	s_nop 0
	v_cvt_pk_bf16_f32 v136, v138, v139
	v_fmamk_f32 v138, v191, 0x42ac0000, v190
	v_fmamk_f32 v139, v191, 0x42ae0000, v190
	v_exp_f32_e32 v138, v138
	v_exp_f32_e32 v139, v139
	v_lshlrev_b32_e32 v140, 16, v137
	v_and_b32_e32 v141, 0xffff0000, v137
	v_pk_mul_f32 v[138:139], v[138:139], v[140:141]
	s_nop 0
	v_cvt_pk_bf16_f32 v137, v138, v139
	s_waitcnt vmcnt(0)
	v_mov_b32_e32 v138, v242
	v_mov_b32_e32 v139, v243
	v_mov_b32_e32 v140, v244
	v_mov_b32_e32 v141, v245
	v_lshlrev_b32_e32 v166, 16, v138
	v_and_b32_e32 v167, 0xffff0000, v138
	v_pk_mul_f32 v[144:145], v[144:145], v[166:167]
	v_lshlrev_b32_e32 v166, 16, v139
	v_cvt_pk_bf16_f32 v138, v144, v145
	v_fmamk_f32 v144, v191, 0x42c40000, v190
	v_fmamk_f32 v145, v191, 0x42c60000, v190
	v_exp_f32_e32 v144, v144
	v_exp_f32_e32 v145, v145
	v_and_b32_e32 v167, 0xffff0000, v139
	v_pk_mul_f32 v[144:145], v[144:145], v[166:167]
	s_nop 0
	v_cvt_pk_bf16_f32 v139, v144, v145
	v_fmamk_f32 v144, v191, 0x42c80000, v190
	v_fmamk_f32 v145, v191, 0x42ca0000, v190
	v_exp_f32_e32 v144, v144
	v_exp_f32_e32 v145, v145
	v_lshlrev_b32_e32 v166, 16, v140
	v_and_b32_e32 v167, 0xffff0000, v140
	v_pk_mul_f32 v[144:145], v[144:145], v[166:167]
	s_nop 0
	v_cvt_pk_bf16_f32 v140, v144, v145
	v_fmamk_f32 v144, v191, 0x42cc0000, v190
	v_fmamk_f32 v145, v191, 0x42ce0000, v190
	v_exp_f32_e32 v144, v144
	v_exp_f32_e32 v145, v145
	v_lshlrev_b32_e32 v166, 16, v141
	v_and_b32_e32 v167, 0xffff0000, v141
	v_pk_mul_f32 v[144:145], v[144:145], v[166:167]
	s_nop 0
	v_cvt_pk_bf16_f32 v141, v144, v145
	v_exp_f32_e32 v166, v153
	v_fmamk_f32 v153, v191, 0x42e20000, v190
	v_exp_f32_e32 v167, v153
	v_fmamk_f32 v153, v191, 0x42e40000, v190
	s_waitcnt vmcnt(0)
	v_mov_b32_e32 v142, v246
	v_mov_b32_e32 v143, v247
	v_mov_b32_e32 v144, v248
	v_mov_b32_e32 v145, v249
	v_lshlrev_b32_e32 v168, 16, v142
	v_and_b32_e32 v169, 0xffff0000, v142
	v_pk_mul_f32 v[166:167], v[166:167], v[168:169]
	v_lshlrev_b32_e32 v168, 16, v143
	v_cvt_pk_bf16_f32 v142, v166, v167
	v_exp_f32_e32 v166, v153
	v_fmamk_f32 v153, v191, 0x42e60000, v190
	v_exp_f32_e32 v167, v153
	v_and_b32_e32 v169, 0xffff0000, v143
	v_fmamk_f32 v153, v191, 0x42e80000, v190
	v_pk_mul_f32 v[166:167], v[166:167], v[168:169]
	s_nop 0
	v_cvt_pk_bf16_f32 v143, v166, v167
	v_exp_f32_e32 v166, v153
	v_fmamk_f32 v153, v191, 0x42ea0000, v190
	v_exp_f32_e32 v167, v153
	v_lshlrev_b32_e32 v168, 16, v144
	v_and_b32_e32 v169, 0xffff0000, v144
	v_fmamk_f32 v153, v191, 0x42ec0000, v190
	v_pk_mul_f32 v[166:167], v[166:167], v[168:169]
	v_fmac_f32_e32 v190, 0x42ee0000, v191
	v_cvt_pk_bf16_f32 v144, v166, v167
	v_exp_f32_e32 v166, v153
	v_exp_f32_e32 v167, v190
	v_lshlrev_b32_e32 v168, 16, v145
	v_and_b32_e32 v169, 0xffff0000, v145
	v_pk_mul_f32 v[166:167], v[166:167], v[168:169]
	s_nop 0
	v_cvt_pk_bf16_f32 v145, v166, v167
	ds_read2_b64 v[166:169], v179 offset0:16 offset1:17
	ds_read2_b64 v[170:173], v179 offset0:20 offset1:21
	ds_read2_b64 v[190:193], v179 offset0:24 offset1:25
	ds_read2_b64 v[194:197], v179 offset0:28 offset1:29
	s_waitcnt lgkmcnt(3)
	v_mfma_f32_32x32x16_bf16 v[2:17], v[166:169], v[130:133], v[2:17]
	v_add_u32_e32 v153, 0x2180, v179
	ds_read2_b64 v[166:169], v153 offset1:1
	s_waitcnt lgkmcnt(3)
	v_mfma_f32_32x32x16_bf16 v[2:17], v[170:173], v[134:137], v[2:17]
	v_add_u32_e32 v153, 0x21a0, v179
	ds_read2_b64 v[170:173], v153 offset1:1
	s_waitcnt lgkmcnt(3)
	v_mfma_f32_32x32x16_bf16 v[2:17], v[190:193], v[138:141], v[2:17]
	v_add_u32_e32 v153, 0x21c0, v179
	ds_read2_b64 v[190:193], v153 offset1:1
	s_waitcnt lgkmcnt(3)
	v_mfma_f32_32x32x16_bf16 v[2:17], v[194:197], v[142:145], v[2:17]
	v_add_u32_e32 v153, 0x21e0, v179
	ds_read2_b64 v[194:197], v153 offset1:1
	s_waitcnt lgkmcnt(3)
	v_mfma_f32_32x32x16_bf16 v[18:33], v[166:169], v[130:133], v[18:33]
	v_add_u32_e32 v153, 0x4280, v179
	ds_read2_b64 v[166:169], v153 offset1:1
	s_waitcnt lgkmcnt(3)
	v_mfma_f32_32x32x16_bf16 v[18:33], v[170:173], v[134:137], v[18:33]
	v_add_u32_e32 v153, 0x42a0, v179
	ds_read2_b64 v[170:173], v153 offset1:1
	s_waitcnt lgkmcnt(3)
	v_mfma_f32_32x32x16_bf16 v[18:33], v[190:193], v[138:141], v[18:33]
	v_add_u32_e32 v153, 0x42c0, v179
	ds_read2_b64 v[190:193], v153 offset1:1
	s_waitcnt lgkmcnt(3)
	v_mfma_f32_32x32x16_bf16 v[18:33], v[194:197], v[142:145], v[18:33]
	v_add_u32_e32 v153, 0x42e0, v179
	ds_read2_b64 v[194:197], v153 offset1:1
	s_waitcnt lgkmcnt(3)
	v_mfma_f32_32x32x16_bf16 v[34:49], v[166:169], v[130:133], v[34:49]
	v_add_u32_e32 v153, 0x6380, v179
	ds_read2_b64 v[166:169], v153 offset1:1
	s_waitcnt lgkmcnt(3)
	v_mfma_f32_32x32x16_bf16 v[34:49], v[170:173], v[134:137], v[34:49]
	v_add_u32_e32 v153, 0x63a0, v179
	ds_read2_b64 v[170:173], v153 offset1:1
	s_waitcnt lgkmcnt(3)
	v_mfma_f32_32x32x16_bf16 v[34:49], v[190:193], v[138:141], v[34:49]
	v_add_u32_e32 v153, 0x63c0, v179
	ds_read2_b64 v[190:193], v153 offset1:1
	s_waitcnt lgkmcnt(3)
	v_mfma_f32_32x32x16_bf16 v[34:49], v[194:197], v[142:145], v[34:49]
	v_add_u32_e32 v153, 0x63e0, v179
	ds_read2_b64 v[194:197], v153 offset1:1
	s_waitcnt lgkmcnt(3)
	v_mfma_f32_32x32x16_bf16 v[50:65], v[166:169], v[130:133], v[50:65]
	v_add_u32_e32 v153, 0x8480, v179
	ds_read2_b64 v[166:169], v153 offset1:1
	s_waitcnt lgkmcnt(3)
	v_mfma_f32_32x32x16_bf16 v[50:65], v[170:173], v[134:137], v[50:65]
	v_add_u32_e32 v153, 0x84a0, v179
	ds_read2_b64 v[170:173], v153 offset1:1
	s_waitcnt lgkmcnt(3)
	v_mfma_f32_32x32x16_bf16 v[50:65], v[190:193], v[138:141], v[50:65]
	v_add_u32_e32 v153, 0x84c0, v179
	ds_read2_b64 v[190:193], v153 offset1:1
	s_waitcnt lgkmcnt(3)
	v_mfma_f32_32x32x16_bf16 v[50:65], v[194:197], v[142:145], v[50:65]
	v_add_u32_e32 v153, 0x84e0, v179
	ds_read2_b64 v[194:197], v153 offset1:1
	s_waitcnt lgkmcnt(3)
	v_mfma_f32_32x32x16_bf16 v[66:81], v[166:169], v[130:133], v[66:81]
	v_add_u32_e32 v153, 0xa580, v179
	ds_read2_b64 v[166:169], v153 offset1:1
	s_waitcnt lgkmcnt(3)
	v_mfma_f32_32x32x16_bf16 v[66:81], v[170:173], v[134:137], v[66:81]
	v_add_u32_e32 v153, 0xa5a0, v179
	ds_read2_b64 v[170:173], v153 offset1:1
	s_waitcnt lgkmcnt(3)
	v_mfma_f32_32x32x16_bf16 v[66:81], v[190:193], v[138:141], v[66:81]
	v_add_u32_e32 v153, 0xa5c0, v179
	ds_read2_b64 v[190:193], v153 offset1:1
	s_waitcnt lgkmcnt(3)
	v_mfma_f32_32x32x16_bf16 v[66:81], v[194:197], v[142:145], v[66:81]
	v_add_u32_e32 v153, 0xa5e0, v179
	ds_read2_b64 v[194:197], v153 offset1:1
	s_waitcnt lgkmcnt(3)
	v_mfma_f32_32x32x16_bf16 v[82:97], v[166:169], v[130:133], v[82:97]
	v_add_u32_e32 v153, 0xc680, v179
	ds_read2_b64 v[166:169], v153 offset1:1
	s_waitcnt lgkmcnt(3)
	v_mfma_f32_32x32x16_bf16 v[82:97], v[170:173], v[134:137], v[82:97]
	v_add_u32_e32 v153, 0xc6a0, v179
	ds_read2_b64 v[170:173], v153 offset1:1
	s_waitcnt lgkmcnt(3)
	v_mfma_f32_32x32x16_bf16 v[82:97], v[190:193], v[138:141], v[82:97]
	v_add_u32_e32 v153, 0xc6c0, v179
	ds_read2_b64 v[190:193], v153 offset1:1
	s_waitcnt lgkmcnt(3)
	v_mfma_f32_32x32x16_bf16 v[82:97], v[194:197], v[142:145], v[82:97]
	v_add_u32_e32 v153, 0xc6e0, v179
	ds_read2_b64 v[194:197], v153 offset1:1
	s_waitcnt lgkmcnt(3)
	v_mfma_f32_32x32x16_bf16 v[98:113], v[166:169], v[130:133], v[98:113]
	v_add_u32_e32 v153, 0xe780, v179
	ds_read2_b64 v[166:169], v153 offset1:1
	s_waitcnt lgkmcnt(3)
	v_mfma_f32_32x32x16_bf16 v[98:113], v[170:173], v[134:137], v[98:113]
	v_add_u32_e32 v153, 0xe7a0, v179
	ds_read2_b64 v[170:173], v153 offset1:1
	s_waitcnt lgkmcnt(3)
	v_mfma_f32_32x32x16_bf16 v[98:113], v[190:193], v[138:141], v[98:113]
	v_add_u32_e32 v153, 0xe7c0, v179
	ds_read2_b64 v[190:193], v153 offset1:1
	s_waitcnt lgkmcnt(3)
	v_mfma_f32_32x32x16_bf16 v[98:113], v[194:197], v[142:145], v[98:113]
	v_add_u32_e32 v153, 0xe7e0, v179
	ds_read2_b64 v[194:197], v153 offset1:1
	s_waitcnt lgkmcnt(3)
	v_mfma_f32_32x32x16_bf16 v[114:129], v[166:169], v[130:133], v[114:129]
	s_waitcnt lgkmcnt(2)
	v_mfma_f32_32x32x16_bf16 v[114:129], v[170:173], v[134:137], v[114:129]
	s_waitcnt lgkmcnt(1)
	v_mfma_f32_32x32x16_bf16 v[114:129], v[190:193], v[138:141], v[114:129]
	s_waitcnt lgkmcnt(0)
	v_mfma_f32_32x32x16_bf16 v[114:129], v[194:197], v[142:145], v[114:129]
	s_add_i32 s66, s66, 1
	s_add_i32 s67, s67, -1
	s_cmp_eq_u32 s67, -1
	s_cbranch_scc0 .LBB0_327
	s_and_b64 vcc, exec, s[4:5]
	s_mov_b64 s[4:5], -1
	s_cbranch_vccnz .LBB0_330
	s_mov_b64 s[4:5], 0
